# GEMM K-loops (P1,P3,P4,P5,P6): loop counter / pointer SALU and exit test hoisted in front of the loop-back s_barrier
# speedup vs baseline: 1.0003x; 1.0003x over previous
; #define PG8_STAGE(bufoff, gbase, voff) do { _Pragma("unroll") for (int _i = 0; _i < 2; ++_i) \
;         __builtin_amdgcn_global_load_lds((const unsigned*)((const char*)(gbase) + (voff)[_i]), (LAS unsigned*)(lds + (bufoff) + ldsw + _i * 8192), 16, 0, 0); } while (0)
; #define PG8_LDA(dst, b, h) do { _Pragma("unroll") for (int m = 0; m < 4; ++m) _Pragma("unroll") for (int k = 0; k < 2; ++k) dst[m][k] = *(const LAS bf16x8*)(lds + PG8_SA(b, h) + aoff + m * 2048 + k * 1024); } while (0)
; #define PG8_LDB(dst, b, h) do { _Pragma("unroll") for (int n = 0; n < 2; ++n) _Pragma("unroll") for (int k = 0; k < 2; ++k) dst[n][k] = *(const LAS bf16x8*)(lds + PG8_SB(b, h) + boff + n * 2048 + k * 1024); } while (0)
; #define PG8_MMA(ai, bj, At, Bt) do { __builtin_amdgcn_s_setprio(1); _Pragma("unroll") for (int m = 0; m < 4; ++m) _Pragma("unroll") for (int n = 0; n < 2; ++n) _Pragma("unroll") for (int k = 0; k < 2; ++k) \
;         acc[ai][bj][m][n] = __builtin_amdgcn_mfma_f32_16x16x32_bf16(Bt[n][k], At[m][k], acc[ai][bj][m][n], 0, 0, 0); __builtin_amdgcn_s_setprio(0); } while (0)
; #define PG8_WAIT_V(n) asm volatile("s_waitcnt vmcnt(" #n ")" ::: "memory")
; #define PG8_WAIT_L(n) asm volatile("s_waitcnt lgkmcnt(" #n ")" ::: "memory")
; #define PG8_BAR __builtin_amdgcn_s_barrier()
; #define PG8_SCHED __builtin_amdgcn_sched_barrier(0)
; template <class Epi, class Sched>
; __device__ __forceinline__ void gemm_phase(LAS unsigned char* lds, const int K, const Sched& S, const Epi& E) {
;     ...
;             const char* a1 = cA + (size_t)(t + 1) * kstep;
;             const char* a2 = last ? nA : cA + (size_t)(t + 2) * kstep; const char* b2 = last ? nB : cB + (size_t)(t + 2) * kstep;
;             const char* a3 = a2 + kstep; const char* b3 = b2 + kstep;
;             PG8_LDB(B0, 0, 0); PG8_LDB(B1, 0, 1); PG8_SCHED; PG8_LDA(At, 0, 0); PG8_STAGE(PG8_SA(1, 1), a1 + hstep, voffA);
;             PG8_WAIT_V(8); PG8_WAIT_L(0); PG8_BAR; PG8_MMA(0, 0, At, B0); PG8_MMA(0, 1, At, B1); PG8_BAR; PG8_SCHED;
;             PG8_LDA(At, 0, 1); PG8_STAGE(PG8_SB(0, 0), b2, voffB); PG8_STAGE(PG8_SB(0, 1), b2 + hstep, voffB); PG8_STAGE(PG8_SA(0, 0), a2, voffA);
;             PG8_WAIT_V(8); PG8_WAIT_L(0); PG8_BAR; PG8_MMA(1, 0, At, B0); PG8_MMA(1, 1, At, B1); PG8_BAR; PG8_SCHED;
.LBB0_126:
	ds_read_b128 v[130:133], v159
	ds_read_b128 v[150:153], v160
	ds_read_b128 v[154:157], v161
	ds_read_b128 v[176:179], v162
	ds_read_b128 v[180:183], v163
	ds_read_b128 v[184:187], v164
	ds_read_b128 v[188:191], v165
	ds_read_b128 v[192:195], v166
	s_add_u32 s40, s74, 0xfffc0080
	s_addc_u32 s41, s75, -1
	s_cmp_eq_u32 vcc_hi, 12
	s_cselect_b32 s79, s7, s41
	s_cselect_b32 s78, s9, s40
	s_cselect_b32 s77, s43, vcc_lo
	s_cselect_b32 s76, s65, s67
	s_mov_b32 m0, s88
	v_lshl_add_u64 v[228:229], s[74:75], 0, v[146:147]
	ds_read_b128 v[196:199], v145
	ds_read_b128 v[200:203], v145 offset:1024
	ds_read_b128 v[204:207], v145 offset:2048
	ds_read_b128 v[208:211], v145 offset:3072
	ds_read_b128 v[212:215], v145 offset:4096
	ds_read_b128 v[216:219], v145 offset:5120
	ds_read_b128 v[220:223], v145 offset:6144
	ds_read_b128 v[224:227], v145 offset:7168
	global_load_lds_dwordx4 v[228:229], off
	v_lshl_add_u64 v[228:229], s[74:75], 0, v[148:149]
	s_mov_b32 m0, s89
	s_nop 0
	global_load_lds_dwordx4 v[228:229], off
	s_waitcnt vmcnt(8)
	s_waitcnt lgkmcnt(0)
	s_barrier
	s_setprio 1
	s_waitcnt lgkmcnt(0)
	v_mfma_f32_16x16x32_bf16 v[126:129], v[130:133], v[196:199], v[126:129]
	v_mfma_f32_16x16x32_bf16 v[122:125], v[154:157], v[196:199], v[122:125]
	v_mfma_f32_16x16x32_bf16 v[118:121], v[130:133], v[204:207], v[118:121]
	v_mfma_f32_16x16x32_bf16 v[110:113], v[154:157], v[204:207], v[110:113]
	v_mfma_f32_16x16x32_bf16 v[102:105], v[130:133], v[212:215], v[102:105]
	v_mfma_f32_16x16x32_bf16 v[94:97], v[154:157], v[212:215], v[94:97]
	v_mfma_f32_16x16x32_bf16 v[86:89], v[130:133], v[220:223], v[86:89]
	v_mfma_f32_16x16x32_bf16 v[78:81], v[154:157], v[220:223], v[78:81]
	v_mfma_f32_16x16x32_bf16 v[126:129], v[150:153], v[200:203], v[126:129]
	v_mfma_f32_16x16x32_bf16 v[122:125], v[176:179], v[200:203], v[122:125]
	v_mfma_f32_16x16x32_bf16 v[118:121], v[150:153], v[208:211], v[118:121]
	v_mfma_f32_16x16x32_bf16 v[110:113], v[176:179], v[208:211], v[110:113]
	v_mfma_f32_16x16x32_bf16 v[102:105], v[150:153], v[216:219], v[102:105]
	v_mfma_f32_16x16x32_bf16 v[94:97], v[176:179], v[216:219], v[94:97]
	v_mfma_f32_16x16x32_bf16 v[86:89], v[150:153], v[224:227], v[86:89]
	v_mfma_f32_16x16x32_bf16 v[78:81], v[176:179], v[224:227], v[78:81]
	s_setprio 0
	s_setprio 1
	v_mfma_f32_16x16x32_bf16 v[114:117], v[180:183], v[196:199], v[114:117]
	v_mfma_f32_16x16x32_bf16 v[106:109], v[188:191], v[196:199], v[106:109]
	v_mfma_f32_16x16x32_bf16 v[98:101], v[180:183], v[204:207], v[98:101]
	v_mfma_f32_16x16x32_bf16 v[90:93], v[188:191], v[204:207], v[90:93]
	v_mfma_f32_16x16x32_bf16 v[82:85], v[180:183], v[212:215], v[82:85]
	v_mfma_f32_16x16x32_bf16 v[74:77], v[188:191], v[212:215], v[74:77]
	v_mfma_f32_16x16x32_bf16 v[70:73], v[180:183], v[220:223], v[70:73]
	v_mfma_f32_16x16x32_bf16 v[66:69], v[188:191], v[220:223], v[66:69]
	v_mfma_f32_16x16x32_bf16 v[114:117], v[184:187], v[200:203], v[114:117]
	v_mfma_f32_16x16x32_bf16 v[106:109], v[192:195], v[200:203], v[106:109]
	v_mfma_f32_16x16x32_bf16 v[98:101], v[184:187], v[208:211], v[98:101]
	v_mfma_f32_16x16x32_bf16 v[90:93], v[192:195], v[208:211], v[90:93]
	v_mfma_f32_16x16x32_bf16 v[82:85], v[184:187], v[216:219], v[82:85]
	v_mfma_f32_16x16x32_bf16 v[74:77], v[192:195], v[216:219], v[74:77]
	v_mfma_f32_16x16x32_bf16 v[70:73], v[184:187], v[224:227], v[70:73]
	v_mfma_f32_16x16x32_bf16 v[66:69], v[192:195], v[224:227], v[66:69]
	s_setprio 0
	s_barrier
	s_mov_b32 m0, s35
	v_lshl_add_u64 v[228:229], s[76:77], 0, v[136:137]
	s_add_u32 s40, s76, 0x40000
	ds_read_b128 v[196:199], v145 offset:16384
	ds_read_b128 v[200:203], v145 offset:17408
	ds_read_b128 v[204:207], v145 offset:18432
	ds_read_b128 v[208:211], v145 offset:19456
	ds_read_b128 v[212:215], v145 offset:20480
	ds_read_b128 v[216:219], v145 offset:21504
	ds_read_b128 v[220:223], v145 offset:22528
	ds_read_b128 v[224:227], v145 offset:23552
	global_load_lds_dwordx4 v[228:229], off
	v_lshl_add_u64 v[230:231], s[76:77], 0, v[140:141]
	s_mov_b32 m0, s36
	s_addc_u32 s41, s77, 0
	global_load_lds_dwordx4 v[230:231], off
	v_lshl_add_u64 v[232:233], s[40:41], 0, v[136:137]
	s_mov_b32 m0, s37
	v_lshl_add_u64 v[234:235], s[78:79], 0, v[138:139]
	global_load_lds_dwordx4 v[232:233], off
	v_lshl_add_u64 v[232:233], s[40:41], 0, v[140:141]
	s_mov_b32 m0, s38
	s_nop 0
	global_load_lds_dwordx4 v[232:233], off
	v_lshl_add_u64 v[232:233], s[78:79], 0, v[134:135]
	s_mov_b32 m0, s34
	s_nop 0
	global_load_lds_dwordx4 v[232:233], off
	s_mov_b32 m0, s39
	s_nop 0
	global_load_lds_dwordx4 v[234:235], off
	s_waitcnt vmcnt(8)
	s_waitcnt lgkmcnt(0)
	s_barrier
; #define PG8_STAGE(bufoff, gbase, voff) do { _Pragma("unroll") for (int _i = 0; _i < 2; ++_i) \
;         __builtin_amdgcn_global_load_lds((const unsigned*)((const char*)(gbase) + (voff)[_i]), (LAS unsigned*)(lds + (bufoff) + ldsw + _i * 8192), 16, 0, 0); } while (0)
; #define PG8_LDA(dst, b, h) do { _Pragma("unroll") for (int m = 0; m < 4; ++m) _Pragma("unroll") for (int k = 0; k < 2; ++k) dst[m][k] = *(const LAS bf16x8*)(lds + PG8_SA(b, h) + aoff + m * 2048 + k * 1024); } while (0)
; #define PG8_LDB(dst, b, h) do { _Pragma("unroll") for (int n = 0; n < 2; ++n) _Pragma("unroll") for (int k = 0; k < 2; ++k) dst[n][k] = *(const LAS bf16x8*)(lds + PG8_SB(b, h) + boff + n * 2048 + k * 1024); } while (0)
; #define PG8_MMA(ai, bj, At, Bt) do { __builtin_amdgcn_s_setprio(1); _Pragma("unroll") for (int m = 0; m < 4; ++m) _Pragma("unroll") for (int n = 0; n < 2; ++n) _Pragma("unroll") for (int k = 0; k < 2; ++k) \
;         acc[ai][bj][m][n] = __builtin_amdgcn_mfma_f32_16x16x32_bf16(Bt[n][k], At[m][k], acc[ai][bj][m][n], 0, 0, 0); __builtin_amdgcn_s_setprio(0); } while (0)
; #define PG8_WAIT_V(n) asm volatile("s_waitcnt vmcnt(" #n ")" ::: "memory")
; #define PG8_WAIT_L(n) asm volatile("s_waitcnt lgkmcnt(" #n ")" ::: "memory")
; #define PG8_BAR __builtin_amdgcn_s_barrier()
; #define PG8_SCHED __builtin_amdgcn_sched_barrier(0)
; template <class Epi, class Sched>
; __device__ __forceinline__ void gemm_phase(LAS unsigned char* lds, const int K, const Sched& S, const Epi& E) {
;     ...
;             PG8_WAIT_V(8); PG8_WAIT_L(0); PG8_BAR; PG8_MMA(1, 0, At, B0); PG8_MMA(1, 1, At, B1); PG8_BAR; PG8_SCHED;
;             PG8_LDB(B0, 1, 0); PG8_LDB(B1, 1, 1); PG8_SCHED; PG8_LDA(At, 1, 0); PG8_STAGE(PG8_SA(0, 1), a2 + hstep, voffA);
;             PG8_WAIT_V(8); PG8_WAIT_L(0); PG8_BAR; PG8_MMA(0, 0, At, B0); PG8_MMA(0, 1, At, B1); PG8_BAR; PG8_SCHED;
	s_setprio 1
	s_waitcnt lgkmcnt(0)
	v_mfma_f32_16x16x32_bf16 v[62:65], v[130:133], v[196:199], v[62:65]
	v_mfma_f32_16x16x32_bf16 v[58:61], v[154:157], v[196:199], v[58:61]
	v_mfma_f32_16x16x32_bf16 v[54:57], v[130:133], v[204:207], v[54:57]
	v_mfma_f32_16x16x32_bf16 v[46:49], v[154:157], v[204:207], v[46:49]
	v_mfma_f32_16x16x32_bf16 v[38:41], v[130:133], v[212:215], v[38:41]
	v_mfma_f32_16x16x32_bf16 v[30:33], v[154:157], v[212:215], v[30:33]
	v_mfma_f32_16x16x32_bf16 v[22:25], v[130:133], v[220:223], v[22:25]
	v_mfma_f32_16x16x32_bf16 v[14:17], v[154:157], v[220:223], v[14:17]
	v_mfma_f32_16x16x32_bf16 v[62:65], v[150:153], v[200:203], v[62:65]
	v_mfma_f32_16x16x32_bf16 v[58:61], v[176:179], v[200:203], v[58:61]
	v_mfma_f32_16x16x32_bf16 v[54:57], v[150:153], v[208:211], v[54:57]
	v_mfma_f32_16x16x32_bf16 v[46:49], v[176:179], v[208:211], v[46:49]
	v_mfma_f32_16x16x32_bf16 v[38:41], v[150:153], v[216:219], v[38:41]
	v_mfma_f32_16x16x32_bf16 v[30:33], v[176:179], v[216:219], v[30:33]
	v_mfma_f32_16x16x32_bf16 v[22:25], v[150:153], v[224:227], v[22:25]
	v_mfma_f32_16x16x32_bf16 v[14:17], v[176:179], v[224:227], v[14:17]
	s_setprio 0
	s_setprio 1
	v_mfma_f32_16x16x32_bf16 v[50:53], v[180:183], v[196:199], v[50:53]
	v_mfma_f32_16x16x32_bf16 v[42:45], v[188:191], v[196:199], v[42:45]
	v_mfma_f32_16x16x32_bf16 v[34:37], v[180:183], v[204:207], v[34:37]
	v_mfma_f32_16x16x32_bf16 v[26:29], v[188:191], v[204:207], v[26:29]
	v_mfma_f32_16x16x32_bf16 v[18:21], v[180:183], v[212:215], v[18:21]
	v_mfma_f32_16x16x32_bf16 v[10:13], v[188:191], v[212:215], v[10:13]
	v_mfma_f32_16x16x32_bf16 v[6:9], v[180:183], v[220:223], v[6:9]
	v_mfma_f32_16x16x32_bf16 v[2:5], v[188:191], v[220:223], v[2:5]
	v_mfma_f32_16x16x32_bf16 v[50:53], v[184:187], v[200:203], v[50:53]
	v_mfma_f32_16x16x32_bf16 v[42:45], v[192:195], v[200:203], v[42:45]
	v_mfma_f32_16x16x32_bf16 v[34:37], v[184:187], v[208:211], v[34:37]
	v_mfma_f32_16x16x32_bf16 v[26:29], v[192:195], v[208:211], v[26:29]
	v_mfma_f32_16x16x32_bf16 v[18:21], v[184:187], v[216:219], v[18:21]
	v_mfma_f32_16x16x32_bf16 v[10:13], v[192:195], v[216:219], v[10:13]
	v_mfma_f32_16x16x32_bf16 v[6:9], v[184:187], v[224:227], v[6:9]
	v_mfma_f32_16x16x32_bf16 v[2:5], v[192:195], v[224:227], v[2:5]
	s_setprio 0
	s_barrier
	ds_read_b128 v[130:133], v167
	ds_read_b128 v[150:153], v168
	ds_read_b128 v[154:157], v169
	ds_read_b128 v[176:179], v170
	ds_read_b128 v[180:183], v171
	ds_read_b128 v[184:187], v172
	ds_read_b128 v[188:191], v173
	ds_read_b128 v[192:195], v174
	s_add_u32 s40, s78, 0x40000
	s_addc_u32 s41, s79, 0
	s_mov_b32 m0, s55
	v_lshl_add_u64 v[236:237], s[40:41], 0, v[134:135]
	ds_read_b128 v[196:199], v145 offset:32768
	ds_read_b128 v[200:203], v145 offset:33792
	ds_read_b128 v[204:207], v145 offset:34816
	ds_read_b128 v[208:211], v145 offset:35840
	ds_read_b128 v[212:215], v145 offset:36864
	ds_read_b128 v[216:219], v145 offset:37888
	ds_read_b128 v[220:223], v145 offset:38912
	ds_read_b128 v[224:227], v145 offset:39936
	global_load_lds_dwordx4 v[236:237], off
	v_lshl_add_u64 v[236:237], s[40:41], 0, v[138:139]
	s_mov_b32 m0, s63
	s_nop 0
	global_load_lds_dwordx4 v[236:237], off
	s_waitcnt vmcnt(8)
	s_waitcnt lgkmcnt(0)
	s_barrier
	s_setprio 1
	s_waitcnt lgkmcnt(0)
	v_mfma_f32_16x16x32_bf16 v[126:129], v[130:133], v[196:199], v[126:129]
	v_mfma_f32_16x16x32_bf16 v[122:125], v[154:157], v[196:199], v[122:125]
	v_mfma_f32_16x16x32_bf16 v[118:121], v[130:133], v[204:207], v[118:121]
	v_mfma_f32_16x16x32_bf16 v[110:113], v[154:157], v[204:207], v[110:113]
	v_mfma_f32_16x16x32_bf16 v[102:105], v[130:133], v[212:215], v[102:105]
	v_mfma_f32_16x16x32_bf16 v[94:97], v[154:157], v[212:215], v[94:97]
	v_mfma_f32_16x16x32_bf16 v[86:89], v[130:133], v[220:223], v[86:89]
	v_mfma_f32_16x16x32_bf16 v[78:81], v[154:157], v[220:223], v[78:81]
	v_mfma_f32_16x16x32_bf16 v[126:129], v[150:153], v[200:203], v[126:129]
	v_mfma_f32_16x16x32_bf16 v[122:125], v[176:179], v[200:203], v[122:125]
	v_mfma_f32_16x16x32_bf16 v[118:121], v[150:153], v[208:211], v[118:121]
	v_mfma_f32_16x16x32_bf16 v[110:113], v[176:179], v[208:211], v[110:113]
	v_mfma_f32_16x16x32_bf16 v[102:105], v[150:153], v[216:219], v[102:105]
	v_mfma_f32_16x16x32_bf16 v[94:97], v[176:179], v[216:219], v[94:97]
	v_mfma_f32_16x16x32_bf16 v[86:89], v[150:153], v[224:227], v[86:89]
	v_mfma_f32_16x16x32_bf16 v[78:81], v[176:179], v[224:227], v[78:81]
	s_setprio 0
	s_setprio 1
	v_mfma_f32_16x16x32_bf16 v[114:117], v[180:183], v[196:199], v[114:117]
	v_mfma_f32_16x16x32_bf16 v[106:109], v[188:191], v[196:199], v[106:109]
	v_mfma_f32_16x16x32_bf16 v[98:101], v[180:183], v[204:207], v[98:101]
	v_mfma_f32_16x16x32_bf16 v[90:93], v[188:191], v[204:207], v[90:93]
	v_mfma_f32_16x16x32_bf16 v[82:85], v[180:183], v[212:215], v[82:85]
	v_mfma_f32_16x16x32_bf16 v[74:77], v[188:191], v[212:215], v[74:77]
	v_mfma_f32_16x16x32_bf16 v[70:73], v[180:183], v[220:223], v[70:73]
	v_mfma_f32_16x16x32_bf16 v[66:69], v[188:191], v[220:223], v[66:69]
	v_mfma_f32_16x16x32_bf16 v[114:117], v[184:187], v[200:203], v[114:117]
	v_mfma_f32_16x16x32_bf16 v[106:109], v[192:195], v[200:203], v[106:109]
	v_mfma_f32_16x16x32_bf16 v[98:101], v[184:187], v[208:211], v[98:101]
	v_mfma_f32_16x16x32_bf16 v[90:93], v[192:195], v[208:211], v[90:93]
	v_mfma_f32_16x16x32_bf16 v[82:85], v[184:187], v[216:219], v[82:85]
	v_mfma_f32_16x16x32_bf16 v[74:77], v[192:195], v[216:219], v[74:77]
	v_mfma_f32_16x16x32_bf16 v[70:73], v[184:187], v[224:227], v[70:73]
	v_mfma_f32_16x16x32_bf16 v[66:69], v[192:195], v[224:227], v[66:69]
	s_setprio 0
	s_barrier
; #define PG8_STAGE(bufoff, gbase, voff) do { _Pragma("unroll") for (int _i = 0; _i < 2; ++_i) \
;         __builtin_amdgcn_global_load_lds((const unsigned*)((const char*)(gbase) + (voff)[_i]), (LAS unsigned*)(lds + (bufoff) + ldsw + _i * 8192), 16, 0, 0); } while (0)
; #define PG8_LDA(dst, b, h) do { _Pragma("unroll") for (int m = 0; m < 4; ++m) _Pragma("unroll") for (int k = 0; k < 2; ++k) dst[m][k] = *(const LAS bf16x8*)(lds + PG8_SA(b, h) + aoff + m * 2048 + k * 1024); } while (0)
; #define PG8_MMA(ai, bj, At, Bt) do { __builtin_amdgcn_s_setprio(1); _Pragma("unroll") for (int m = 0; m < 4; ++m) _Pragma("unroll") for (int n = 0; n < 2; ++n) _Pragma("unroll") for (int k = 0; k < 2; ++k) \
;         acc[ai][bj][m][n] = __builtin_amdgcn_mfma_f32_16x16x32_bf16(Bt[n][k], At[m][k], acc[ai][bj][m][n], 0, 0, 0); __builtin_amdgcn_s_setprio(0); } while (0)
; #define PG8_WAIT_V(n) asm volatile("s_waitcnt vmcnt(" #n ")" ::: "memory")
; #define PG8_WAIT_L(n) asm volatile("s_waitcnt lgkmcnt(" #n ")" ::: "memory")
; #define PG8_BAR __builtin_amdgcn_s_barrier()
; #define PG8_SCHED __builtin_amdgcn_sched_barrier(0)
; template <class Epi, class Sched>
; __device__ __forceinline__ void gemm_phase(LAS unsigned char* lds, const int K, const Sched& S, const Epi& E) {
;     ...
;             PG8_LDA(At, 1, 1); PG8_STAGE(PG8_SB(1, 0), b3, voffB); PG8_STAGE(PG8_SB(1, 1), b3 + hstep, voffB); PG8_STAGE(PG8_SA(1, 0), a3, voffA);
;             PG8_WAIT_V(8); PG8_WAIT_L(0); PG8_BAR; PG8_MMA(1, 0, At, B0); PG8_MMA(1, 1, At, B1); PG8_BAR; PG8_SCHED;
;         }
	s_mov_b32 m0, s82
	v_lshl_add_u64 v[228:229], v[228:229], 0, s[44:45]
	s_add_u32 s40, s76, 0x40080
	ds_read_b128 v[196:199], v145 offset:49152
	ds_read_b128 v[200:203], v145 offset:50176
	ds_read_b128 v[204:207], v145 offset:51200
	ds_read_b128 v[208:211], v145 offset:52224
	ds_read_b128 v[212:215], v145 offset:53248
	ds_read_b128 v[216:219], v145 offset:54272
	ds_read_b128 v[220:223], v145 offset:55296
	ds_read_b128 v[224:227], v145 offset:56320
	global_load_lds_dwordx4 v[228:229], off
	v_lshl_add_u64 v[228:229], v[230:231], 0, s[44:45]
	s_mov_b32 m0, s83
	s_addc_u32 s41, s77, 0
	global_load_lds_dwordx4 v[228:229], off
	v_lshl_add_u64 v[228:229], s[40:41], 0, v[136:137]
	s_mov_b32 m0, s86
	s_nop 0
	global_load_lds_dwordx4 v[228:229], off
	v_lshl_add_u64 v[228:229], s[40:41], 0, v[140:141]
	s_mov_b32 m0, s87
	s_nop 0
	global_load_lds_dwordx4 v[228:229], off
	v_lshl_add_u64 v[228:229], v[232:233], 0, s[44:45]
	s_mov_b32 m0, s84
	s_nop 0
	global_load_lds_dwordx4 v[228:229], off
	v_lshl_add_u64 v[228:229], v[234:235], 0, s[44:45]
	s_mov_b32 m0, s85
	s_nop 0
	global_load_lds_dwordx4 v[228:229], off
	s_waitcnt vmcnt(8)
	s_waitcnt lgkmcnt(0)
	s_barrier
	s_setprio 1
	s_waitcnt lgkmcnt(0)
	v_mfma_f32_16x16x32_bf16 v[62:65], v[130:133], v[196:199], v[62:65]
	v_mfma_f32_16x16x32_bf16 v[58:61], v[154:157], v[196:199], v[58:61]
	v_mfma_f32_16x16x32_bf16 v[54:57], v[130:133], v[204:207], v[54:57]
	v_mfma_f32_16x16x32_bf16 v[46:49], v[154:157], v[204:207], v[46:49]
	v_mfma_f32_16x16x32_bf16 v[38:41], v[130:133], v[212:215], v[38:41]
	v_mfma_f32_16x16x32_bf16 v[30:33], v[154:157], v[212:215], v[30:33]
	v_mfma_f32_16x16x32_bf16 v[22:25], v[130:133], v[220:223], v[22:25]
	v_mfma_f32_16x16x32_bf16 v[14:17], v[154:157], v[220:223], v[14:17]
	v_mfma_f32_16x16x32_bf16 v[62:65], v[150:153], v[200:203], v[62:65]
	v_mfma_f32_16x16x32_bf16 v[58:61], v[176:179], v[200:203], v[58:61]
	v_mfma_f32_16x16x32_bf16 v[54:57], v[150:153], v[208:211], v[54:57]
	v_mfma_f32_16x16x32_bf16 v[46:49], v[176:179], v[208:211], v[46:49]
	v_mfma_f32_16x16x32_bf16 v[38:41], v[150:153], v[216:219], v[38:41]
	v_mfma_f32_16x16x32_bf16 v[30:33], v[176:179], v[216:219], v[30:33]
	v_mfma_f32_16x16x32_bf16 v[22:25], v[150:153], v[224:227], v[22:25]
	v_mfma_f32_16x16x32_bf16 v[14:17], v[176:179], v[224:227], v[14:17]
	s_setprio 0
	s_setprio 1
	v_mfma_f32_16x16x32_bf16 v[50:53], v[180:183], v[196:199], v[50:53]
	v_mfma_f32_16x16x32_bf16 v[42:45], v[188:191], v[196:199], v[42:45]
	v_mfma_f32_16x16x32_bf16 v[34:37], v[180:183], v[204:207], v[34:37]
	v_mfma_f32_16x16x32_bf16 v[26:29], v[188:191], v[204:207], v[26:29]
	v_mfma_f32_16x16x32_bf16 v[18:21], v[180:183], v[212:215], v[18:21]
	v_mfma_f32_16x16x32_bf16 v[10:13], v[188:191], v[212:215], v[10:13]
	v_mfma_f32_16x16x32_bf16 v[6:9], v[180:183], v[220:223], v[6:9]
	v_mfma_f32_16x16x32_bf16 v[2:5], v[188:191], v[220:223], v[2:5]
	v_mfma_f32_16x16x32_bf16 v[50:53], v[184:187], v[200:203], v[50:53]
	v_mfma_f32_16x16x32_bf16 v[42:45], v[192:195], v[200:203], v[42:45]
	v_mfma_f32_16x16x32_bf16 v[34:37], v[184:187], v[208:211], v[34:37]
	v_mfma_f32_16x16x32_bf16 v[26:29], v[192:195], v[208:211], v[26:29]
	v_mfma_f32_16x16x32_bf16 v[18:21], v[184:187], v[216:219], v[18:21]
	v_mfma_f32_16x16x32_bf16 v[10:13], v[192:195], v[216:219], v[10:13]
	v_mfma_f32_16x16x32_bf16 v[6:9], v[184:187], v[224:227], v[6:9]
	v_mfma_f32_16x16x32_bf16 v[2:5], v[192:195], v[224:227], v[2:5]
	s_setprio 0
	s_add_i32 vcc_hi, vcc_hi, 2
	s_add_u32 s74, s74, 0x100
	s_addc_u32 s75, s75, 0
	s_add_u32 s67, s67, 0x100
	s_addc_u32 vcc_lo, vcc_lo, 0
	s_cmp_gt_u32 vcc_hi, 13
	s_barrier
	s_cbranch_scc0 .LBB0_126
	s_and_b64 vcc, exec, s[46:47]
	s_cbranch_vccz .LBB0_129
	s_barrier

; #define PG8_STAGE(bufoff, gbase, voff) do { _Pragma("unroll") for (int _i = 0; _i < 2; ++_i) \
;         __builtin_amdgcn_global_load_lds((const unsigned*)((const char*)(gbase) + (voff)[_i]), (LAS unsigned*)(lds + (bufoff) + ldsw + _i * 8192), 16, 0, 0); } while (0)
; #define PG8_LDA(dst, b, h) do { _Pragma("unroll") for (int m = 0; m < 4; ++m) _Pragma("unroll") for (int k = 0; k < 2; ++k) dst[m][k] = *(const LAS bf16x8*)(lds + PG8_SA(b, h) + aoff + m * 2048 + k * 1024); } while (0)
; #define PG8_LDB(dst, b, h) do { _Pragma("unroll") for (int n = 0; n < 2; ++n) _Pragma("unroll") for (int k = 0; k < 2; ++k) dst[n][k] = *(const LAS bf16x8*)(lds + PG8_SB(b, h) + boff + n * 2048 + k * 1024); } while (0)
; #define PG8_MMA(ai, bj, At, Bt) do { __builtin_amdgcn_s_setprio(1); _Pragma("unroll") for (int m = 0; m < 4; ++m) _Pragma("unroll") for (int n = 0; n < 2; ++n) _Pragma("unroll") for (int k = 0; k < 2; ++k) \
;         acc[ai][bj][m][n] = __builtin_amdgcn_mfma_f32_16x16x32_bf16(Bt[n][k], At[m][k], acc[ai][bj][m][n], 0, 0, 0); __builtin_amdgcn_s_setprio(0); } while (0)
; #define PG8_WAIT_V(n) asm volatile("s_waitcnt vmcnt(" #n ")" ::: "memory")
; #define PG8_WAIT_L(n) asm volatile("s_waitcnt lgkmcnt(" #n ")" ::: "memory")
; #define PG8_BAR __builtin_amdgcn_s_barrier()
; #define PG8_SCHED __builtin_amdgcn_sched_barrier(0)
; template <class Epi, class Sched>
; __device__ __forceinline__ void gemm_phase(LAS unsigned char* lds, const int K, const Sched& S, const Epi& E) {
;     ...
;             if (last) E.prefetch(lds, cur, wid, lane);
;             const char* a1 = cA + (size_t)(t + 1) * kstep;
;             const char* a2 = last ? nA : cA + (size_t)(t + 2) * kstep; const char* b2 = last ? nB : cB + (size_t)(t + 2) * kstep;
;             const char* a3 = a2 + kstep; const char* b3 = b2 + kstep;
;             PG8_LDB(B0, 0, 0); PG8_LDB(B1, 0, 1); PG8_SCHED; PG8_LDA(At, 0, 0); PG8_STAGE(PG8_SA(1, 1), a1 + hstep, voffA);
;             PG8_WAIT_V(8); PG8_WAIT_L(0); PG8_BAR; PG8_MMA(0, 0, At, B0); PG8_MMA(0, 1, At, B1); PG8_BAR; PG8_SCHED;
;             PG8_LDA(At, 0, 1); PG8_STAGE(PG8_SB(0, 0), b2, voffB); PG8_STAGE(PG8_SB(0, 1), b2 + hstep, voffB); PG8_STAGE(PG8_SA(0, 0), a2, voffA);
;             PG8_WAIT_V(8); PG8_WAIT_L(0); PG8_BAR; PG8_MMA(1, 0, At, B0); PG8_MMA(1, 1, At, B1); PG8_BAR; PG8_SCHED;
.LBB0_759:
	ds_read_b128 v[130:133], v193
	ds_read_b128 v[134:137], v194
	ds_read_b128 v[138:141], v195
	ds_read_b128 v[142:145], v196
	ds_read_b128 v[146:149], v197
	ds_read_b128 v[150:153], v198
	ds_read_b128 v[154:157], v199
	ds_read_b128 v[158:161], v200
	s_add_u32 s56, s54, 0xfffc0080
	s_addc_u32 s57, s55, -1
	s_cmp_eq_u32 s71, 12
	s_cselect_b32 s59, s49, s57
	s_cselect_b32 s58, s48, s56
	s_cselect_b32 s57, s51, s47
	s_cselect_b32 s56, s50, s7
	s_mov_b32 m0, s63
	v_lshl_add_u64 v[188:189], s[54:55], 0, v[176:177]
	ds_read_b128 v[162:165], v191
	ds_read_b128 v[180:183], v191 offset:1024
	ds_read_b128 v[184:187], v191 offset:2048
	ds_read_b128 v[210:213], v191 offset:3072
	ds_read_b128 v[214:217], v191 offset:4096
	ds_read_b128 v[218:221], v191 offset:5120
	ds_read_b128 v[222:225], v191 offset:6144
	ds_read_b128 v[226:229], v191 offset:7168
	global_load_lds_dwordx4 v[188:189], off
	v_lshl_add_u64 v[188:189], s[54:55], 0, v[178:179]
	s_mov_b32 m0, s64
	s_nop 0
	global_load_lds_dwordx4 v[188:189], off
	s_waitcnt vmcnt(8)
	s_waitcnt lgkmcnt(0)
	s_barrier
	s_setprio 1
	s_waitcnt lgkmcnt(0)
	v_mfma_f32_16x16x32_bf16 v[126:129], v[130:133], v[162:165], v[126:129]
	v_mfma_f32_16x16x32_bf16 v[122:125], v[138:141], v[162:165], v[122:125]
	v_mfma_f32_16x16x32_bf16 v[118:121], v[130:133], v[184:187], v[118:121]
	v_mfma_f32_16x16x32_bf16 v[114:117], v[138:141], v[184:187], v[114:117]
	v_mfma_f32_16x16x32_bf16 v[110:113], v[130:133], v[214:217], v[110:113]
	v_mfma_f32_16x16x32_bf16 v[106:109], v[138:141], v[214:217], v[106:109]
	v_mfma_f32_16x16x32_bf16 v[102:105], v[130:133], v[222:225], v[102:105]
	v_mfma_f32_16x16x32_bf16 v[98:101], v[138:141], v[222:225], v[98:101]
	v_mfma_f32_16x16x32_bf16 v[126:129], v[134:137], v[180:183], v[126:129]
	v_mfma_f32_16x16x32_bf16 v[122:125], v[142:145], v[180:183], v[122:125]
	v_mfma_f32_16x16x32_bf16 v[118:121], v[134:137], v[210:213], v[118:121]
	v_mfma_f32_16x16x32_bf16 v[114:117], v[142:145], v[210:213], v[114:117]
	v_mfma_f32_16x16x32_bf16 v[110:113], v[134:137], v[218:221], v[110:113]
	v_mfma_f32_16x16x32_bf16 v[106:109], v[142:145], v[218:221], v[106:109]
	v_mfma_f32_16x16x32_bf16 v[102:105], v[134:137], v[226:229], v[102:105]
	v_mfma_f32_16x16x32_bf16 v[98:101], v[142:145], v[226:229], v[98:101]
	s_setprio 0
	s_setprio 1
	v_mfma_f32_16x16x32_bf16 v[94:97], v[146:149], v[162:165], v[94:97]
	v_mfma_f32_16x16x32_bf16 v[90:93], v[154:157], v[162:165], v[90:93]
	v_mfma_f32_16x16x32_bf16 v[86:89], v[146:149], v[184:187], v[86:89]
	v_mfma_f32_16x16x32_bf16 v[82:85], v[154:157], v[184:187], v[82:85]
	v_mfma_f32_16x16x32_bf16 v[78:81], v[146:149], v[214:217], v[78:81]
	v_mfma_f32_16x16x32_bf16 v[74:77], v[154:157], v[214:217], v[74:77]
	v_mfma_f32_16x16x32_bf16 v[70:73], v[146:149], v[222:225], v[70:73]
	v_mfma_f32_16x16x32_bf16 v[66:69], v[154:157], v[222:225], v[66:69]
	v_mfma_f32_16x16x32_bf16 v[94:97], v[150:153], v[180:183], v[94:97]
	v_mfma_f32_16x16x32_bf16 v[90:93], v[158:161], v[180:183], v[90:93]
	v_mfma_f32_16x16x32_bf16 v[86:89], v[150:153], v[210:213], v[86:89]
	v_mfma_f32_16x16x32_bf16 v[82:85], v[158:161], v[210:213], v[82:85]
	v_mfma_f32_16x16x32_bf16 v[78:81], v[150:153], v[218:221], v[78:81]
	v_mfma_f32_16x16x32_bf16 v[74:77], v[158:161], v[218:221], v[74:77]
	v_mfma_f32_16x16x32_bf16 v[70:73], v[150:153], v[226:229], v[70:73]
	v_mfma_f32_16x16x32_bf16 v[66:69], v[158:161], v[226:229], v[66:69]
	s_setprio 0
	s_barrier
	s_mov_b32 m0, s29
	v_lshl_add_u64 v[188:189], s[56:57], 0, v[168:169]
	s_add_u32 s72, s56, 0x40000
	ds_read_b128 v[162:165], v191 offset:16384
	ds_read_b128 v[180:183], v191 offset:17408
	ds_read_b128 v[184:187], v191 offset:18432
	ds_read_b128 v[210:213], v191 offset:19456
	ds_read_b128 v[214:217], v191 offset:20480
	ds_read_b128 v[218:221], v191 offset:21504
	ds_read_b128 v[222:225], v191 offset:22528
	ds_read_b128 v[226:229], v191 offset:23552
	global_load_lds_dwordx4 v[188:189], off
	v_lshl_add_u64 v[230:231], s[56:57], 0, v[172:173]
	s_mov_b32 m0, s31
	s_addc_u32 s73, s57, 0
	global_load_lds_dwordx4 v[230:231], off
	v_lshl_add_u64 v[232:233], s[72:73], 0, v[168:169]
	s_mov_b32 m0, s33
	v_lshl_add_u64 v[234:235], s[58:59], 0, v[170:171]
	global_load_lds_dwordx4 v[232:233], off
	v_lshl_add_u64 v[232:233], s[72:73], 0, v[172:173]
	s_mov_b32 m0, s34
	s_nop 0
	global_load_lds_dwordx4 v[232:233], off
	v_lshl_add_u64 v[232:233], s[58:59], 0, v[166:167]
	s_mov_b32 m0, s28
	s_nop 0
	global_load_lds_dwordx4 v[232:233], off
	s_mov_b32 m0, s35
	s_nop 0
	global_load_lds_dwordx4 v[234:235], off
	s_waitcnt vmcnt(8)
	s_waitcnt lgkmcnt(0)
	s_barrier
; #define PG8_STAGE(bufoff, gbase, voff) do { _Pragma("unroll") for (int _i = 0; _i < 2; ++_i) \
;         __builtin_amdgcn_global_load_lds((const unsigned*)((const char*)(gbase) + (voff)[_i]), (LAS unsigned*)(lds + (bufoff) + ldsw + _i * 8192), 16, 0, 0); } while (0)
; #define PG8_LDA(dst, b, h) do { _Pragma("unroll") for (int m = 0; m < 4; ++m) _Pragma("unroll") for (int k = 0; k < 2; ++k) dst[m][k] = *(const LAS bf16x8*)(lds + PG8_SA(b, h) + aoff + m * 2048 + k * 1024); } while (0)
; #define PG8_LDB(dst, b, h) do { _Pragma("unroll") for (int n = 0; n < 2; ++n) _Pragma("unroll") for (int k = 0; k < 2; ++k) dst[n][k] = *(const LAS bf16x8*)(lds + PG8_SB(b, h) + boff + n * 2048 + k * 1024); } while (0)
; #define PG8_MMA(ai, bj, At, Bt) do { __builtin_amdgcn_s_setprio(1); _Pragma("unroll") for (int m = 0; m < 4; ++m) _Pragma("unroll") for (int n = 0; n < 2; ++n) _Pragma("unroll") for (int k = 0; k < 2; ++k) \
;         acc[ai][bj][m][n] = __builtin_amdgcn_mfma_f32_16x16x32_bf16(Bt[n][k], At[m][k], acc[ai][bj][m][n], 0, 0, 0); __builtin_amdgcn_s_setprio(0); } while (0)
; #define PG8_WAIT_V(n) asm volatile("s_waitcnt vmcnt(" #n ")" ::: "memory")
; #define PG8_WAIT_L(n) asm volatile("s_waitcnt lgkmcnt(" #n ")" ::: "memory")
; #define PG8_BAR __builtin_amdgcn_s_barrier()
; #define PG8_SCHED __builtin_amdgcn_sched_barrier(0)
; template <class Epi, class Sched>
; __device__ __forceinline__ void gemm_phase(LAS unsigned char* lds, const int K, const Sched& S, const Epi& E) {
;     ...
;             PG8_WAIT_V(8); PG8_WAIT_L(0); PG8_BAR; PG8_MMA(1, 0, At, B0); PG8_MMA(1, 1, At, B1); PG8_BAR; PG8_SCHED;
;             PG8_LDB(B0, 1, 0); PG8_LDB(B1, 1, 1); PG8_SCHED; PG8_LDA(At, 1, 0); PG8_STAGE(PG8_SA(0, 1), a2 + hstep, voffA);
;             PG8_WAIT_V(8); PG8_WAIT_L(0); PG8_BAR; PG8_MMA(0, 0, At, B0); PG8_MMA(0, 1, At, B1); PG8_BAR; PG8_SCHED;
	s_setprio 1
	s_waitcnt lgkmcnt(0)
	v_mfma_f32_16x16x32_bf16 v[62:65], v[130:133], v[162:165], v[62:65]
	v_mfma_f32_16x16x32_bf16 v[58:61], v[138:141], v[162:165], v[58:61]
	v_mfma_f32_16x16x32_bf16 v[54:57], v[130:133], v[184:187], v[54:57]
	v_mfma_f32_16x16x32_bf16 v[50:53], v[138:141], v[184:187], v[50:53]
	v_mfma_f32_16x16x32_bf16 v[46:49], v[130:133], v[214:217], v[46:49]
	v_mfma_f32_16x16x32_bf16 v[42:45], v[138:141], v[214:217], v[42:45]
	v_mfma_f32_16x16x32_bf16 v[38:41], v[130:133], v[222:225], v[38:41]
	v_mfma_f32_16x16x32_bf16 v[34:37], v[138:141], v[222:225], v[34:37]
	v_mfma_f32_16x16x32_bf16 v[62:65], v[134:137], v[180:183], v[62:65]
	v_mfma_f32_16x16x32_bf16 v[58:61], v[142:145], v[180:183], v[58:61]
	v_mfma_f32_16x16x32_bf16 v[54:57], v[134:137], v[210:213], v[54:57]
	v_mfma_f32_16x16x32_bf16 v[50:53], v[142:145], v[210:213], v[50:53]
	v_mfma_f32_16x16x32_bf16 v[46:49], v[134:137], v[218:221], v[46:49]
	v_mfma_f32_16x16x32_bf16 v[42:45], v[142:145], v[218:221], v[42:45]
	v_mfma_f32_16x16x32_bf16 v[38:41], v[134:137], v[226:229], v[38:41]
	v_mfma_f32_16x16x32_bf16 v[34:37], v[142:145], v[226:229], v[34:37]
	s_setprio 0
	s_setprio 1
	v_mfma_f32_16x16x32_bf16 v[30:33], v[146:149], v[162:165], v[30:33]
	v_mfma_f32_16x16x32_bf16 v[26:29], v[154:157], v[162:165], v[26:29]
	v_mfma_f32_16x16x32_bf16 v[22:25], v[146:149], v[184:187], v[22:25]
	v_mfma_f32_16x16x32_bf16 v[18:21], v[154:157], v[184:187], v[18:21]
	v_mfma_f32_16x16x32_bf16 v[14:17], v[146:149], v[214:217], v[14:17]
	v_mfma_f32_16x16x32_bf16 v[10:13], v[154:157], v[214:217], v[10:13]
	v_mfma_f32_16x16x32_bf16 v[6:9], v[146:149], v[222:225], v[6:9]
	v_mfma_f32_16x16x32_bf16 v[2:5], v[154:157], v[222:225], v[2:5]
	v_mfma_f32_16x16x32_bf16 v[30:33], v[150:153], v[180:183], v[30:33]
	v_mfma_f32_16x16x32_bf16 v[26:29], v[158:161], v[180:183], v[26:29]
	v_mfma_f32_16x16x32_bf16 v[22:25], v[150:153], v[210:213], v[22:25]
	v_mfma_f32_16x16x32_bf16 v[18:21], v[158:161], v[210:213], v[18:21]
	v_mfma_f32_16x16x32_bf16 v[14:17], v[150:153], v[218:221], v[14:17]
	v_mfma_f32_16x16x32_bf16 v[10:13], v[158:161], v[218:221], v[10:13]
	v_mfma_f32_16x16x32_bf16 v[6:9], v[150:153], v[226:229], v[6:9]
	v_mfma_f32_16x16x32_bf16 v[2:5], v[158:161], v[226:229], v[2:5]
	s_setprio 0
	s_barrier
	ds_read_b128 v[130:133], v201
	ds_read_b128 v[134:137], v202
	ds_read_b128 v[138:141], v203
	ds_read_b128 v[142:145], v204
	ds_read_b128 v[146:149], v205
	ds_read_b128 v[150:153], v206
	ds_read_b128 v[154:157], v207
	ds_read_b128 v[158:161], v208
	s_add_u32 s58, s58, 0x40000
	s_addc_u32 s59, s59, 0
	s_mov_b32 m0, s36
	v_lshl_add_u64 v[236:237], s[58:59], 0, v[166:167]
	ds_read_b128 v[162:165], v191 offset:32768
	ds_read_b128 v[180:183], v191 offset:33792
	ds_read_b128 v[184:187], v191 offset:34816
	ds_read_b128 v[210:213], v191 offset:35840
	ds_read_b128 v[214:217], v191 offset:36864
	ds_read_b128 v[218:221], v191 offset:37888
	ds_read_b128 v[222:225], v191 offset:38912
	ds_read_b128 v[226:229], v191 offset:39936
	global_load_lds_dwordx4 v[236:237], off
	v_lshl_add_u64 v[236:237], s[58:59], 0, v[170:171]
	s_mov_b32 m0, s37
	s_nop 0
	global_load_lds_dwordx4 v[236:237], off
	s_waitcnt vmcnt(8)
	s_waitcnt lgkmcnt(0)
	s_barrier
	s_setprio 1
	s_waitcnt lgkmcnt(0)
	v_mfma_f32_16x16x32_bf16 v[126:129], v[130:133], v[162:165], v[126:129]
	v_mfma_f32_16x16x32_bf16 v[122:125], v[138:141], v[162:165], v[122:125]
	v_mfma_f32_16x16x32_bf16 v[118:121], v[130:133], v[184:187], v[118:121]
	v_mfma_f32_16x16x32_bf16 v[114:117], v[138:141], v[184:187], v[114:117]
	v_mfma_f32_16x16x32_bf16 v[110:113], v[130:133], v[214:217], v[110:113]
	v_mfma_f32_16x16x32_bf16 v[106:109], v[138:141], v[214:217], v[106:109]
	v_mfma_f32_16x16x32_bf16 v[102:105], v[130:133], v[222:225], v[102:105]
	v_mfma_f32_16x16x32_bf16 v[98:101], v[138:141], v[222:225], v[98:101]
	v_mfma_f32_16x16x32_bf16 v[126:129], v[134:137], v[180:183], v[126:129]
	v_mfma_f32_16x16x32_bf16 v[122:125], v[142:145], v[180:183], v[122:125]
	v_mfma_f32_16x16x32_bf16 v[118:121], v[134:137], v[210:213], v[118:121]
	v_mfma_f32_16x16x32_bf16 v[114:117], v[142:145], v[210:213], v[114:117]
	v_mfma_f32_16x16x32_bf16 v[110:113], v[134:137], v[218:221], v[110:113]
	v_mfma_f32_16x16x32_bf16 v[106:109], v[142:145], v[218:221], v[106:109]
	v_mfma_f32_16x16x32_bf16 v[102:105], v[134:137], v[226:229], v[102:105]
	v_mfma_f32_16x16x32_bf16 v[98:101], v[142:145], v[226:229], v[98:101]
	s_setprio 0
	s_setprio 1
	v_mfma_f32_16x16x32_bf16 v[94:97], v[146:149], v[162:165], v[94:97]
	v_mfma_f32_16x16x32_bf16 v[90:93], v[154:157], v[162:165], v[90:93]
	v_mfma_f32_16x16x32_bf16 v[86:89], v[146:149], v[184:187], v[86:89]
	v_mfma_f32_16x16x32_bf16 v[82:85], v[154:157], v[184:187], v[82:85]
	v_mfma_f32_16x16x32_bf16 v[78:81], v[146:149], v[214:217], v[78:81]
	v_mfma_f32_16x16x32_bf16 v[74:77], v[154:157], v[214:217], v[74:77]
	v_mfma_f32_16x16x32_bf16 v[70:73], v[146:149], v[222:225], v[70:73]
	v_mfma_f32_16x16x32_bf16 v[66:69], v[154:157], v[222:225], v[66:69]
	v_mfma_f32_16x16x32_bf16 v[94:97], v[150:153], v[180:183], v[94:97]
	v_mfma_f32_16x16x32_bf16 v[90:93], v[158:161], v[180:183], v[90:93]
	v_mfma_f32_16x16x32_bf16 v[86:89], v[150:153], v[210:213], v[86:89]
	v_mfma_f32_16x16x32_bf16 v[82:85], v[158:161], v[210:213], v[82:85]
	v_mfma_f32_16x16x32_bf16 v[78:81], v[150:153], v[218:221], v[78:81]
	v_mfma_f32_16x16x32_bf16 v[74:77], v[158:161], v[218:221], v[74:77]
	v_mfma_f32_16x16x32_bf16 v[70:73], v[150:153], v[226:229], v[70:73]
	v_mfma_f32_16x16x32_bf16 v[66:69], v[158:161], v[226:229], v[66:69]
	s_setprio 0
	s_barrier
; #define PG8_STAGE(bufoff, gbase, voff) do { _Pragma("unroll") for (int _i = 0; _i < 2; ++_i) \
;         __builtin_amdgcn_global_load_lds((const unsigned*)((const char*)(gbase) + (voff)[_i]), (LAS unsigned*)(lds + (bufoff) + ldsw + _i * 8192), 16, 0, 0); } while (0)
; #define PG8_LDA(dst, b, h) do { _Pragma("unroll") for (int m = 0; m < 4; ++m) _Pragma("unroll") for (int k = 0; k < 2; ++k) dst[m][k] = *(const LAS bf16x8*)(lds + PG8_SA(b, h) + aoff + m * 2048 + k * 1024); } while (0)
; #define PG8_MMA(ai, bj, At, Bt) do { __builtin_amdgcn_s_setprio(1); _Pragma("unroll") for (int m = 0; m < 4; ++m) _Pragma("unroll") for (int n = 0; n < 2; ++n) _Pragma("unroll") for (int k = 0; k < 2; ++k) \
;         acc[ai][bj][m][n] = __builtin_amdgcn_mfma_f32_16x16x32_bf16(Bt[n][k], At[m][k], acc[ai][bj][m][n], 0, 0, 0); __builtin_amdgcn_s_setprio(0); } while (0)
; #define PG8_WAIT_V(n) asm volatile("s_waitcnt vmcnt(" #n ")" ::: "memory")
; #define PG8_WAIT_L(n) asm volatile("s_waitcnt lgkmcnt(" #n ")" ::: "memory")
; #define PG8_BAR __builtin_amdgcn_s_barrier()
; #define PG8_SCHED __builtin_amdgcn_sched_barrier(0)
; template <class Epi, class Sched>
; __device__ __forceinline__ void gemm_phase(LAS unsigned char* lds, const int K, const Sched& S, const Epi& E) {
;     ...
;             PG8_LDA(At, 1, 1); PG8_STAGE(PG8_SB(1, 0), b3, voffB); PG8_STAGE(PG8_SB(1, 1), b3 + hstep, voffB); PG8_STAGE(PG8_SA(1, 0), a3, voffA);
;             PG8_WAIT_V(8); PG8_WAIT_L(0); PG8_BAR; PG8_MMA(1, 0, At, B0); PG8_MMA(1, 1, At, B1); PG8_BAR; PG8_SCHED;
;         }
	s_mov_b32 m0, s3
	v_lshl_add_u64 v[188:189], v[188:189], 0, s[40:41]
	s_add_u32 s56, s56, 0x40080
	ds_read_b128 v[162:165], v191 offset:49152
	ds_read_b128 v[180:183], v191 offset:50176
	ds_read_b128 v[184:187], v191 offset:51200
	ds_read_b128 v[210:213], v191 offset:52224
	ds_read_b128 v[214:217], v191 offset:53248
	ds_read_b128 v[218:221], v191 offset:54272
	ds_read_b128 v[222:225], v191 offset:55296
	ds_read_b128 v[226:229], v191 offset:56320
	global_load_lds_dwordx4 v[188:189], off
	v_lshl_add_u64 v[188:189], v[230:231], 0, s[40:41]
	s_mov_b32 m0, s38
	s_addc_u32 s57, s57, 0
	global_load_lds_dwordx4 v[188:189], off
	v_lshl_add_u64 v[188:189], s[56:57], 0, v[168:169]
	s_mov_b32 m0, s61
	s_nop 0
	global_load_lds_dwordx4 v[188:189], off
	v_lshl_add_u64 v[188:189], s[56:57], 0, v[172:173]
	s_mov_b32 m0, s62
	s_nop 0
	global_load_lds_dwordx4 v[188:189], off
	v_lshl_add_u64 v[188:189], v[232:233], 0, s[40:41]
	s_mov_b32 m0, s39
	s_nop 0
	global_load_lds_dwordx4 v[188:189], off
	v_lshl_add_u64 v[188:189], v[234:235], 0, s[40:41]
	s_mov_b32 m0, s60
	s_nop 0
	global_load_lds_dwordx4 v[188:189], off
	s_waitcnt vmcnt(8)
	s_waitcnt lgkmcnt(0)
	s_barrier
	s_setprio 1
	s_waitcnt lgkmcnt(0)
	v_mfma_f32_16x16x32_bf16 v[62:65], v[130:133], v[162:165], v[62:65]
	v_mfma_f32_16x16x32_bf16 v[58:61], v[138:141], v[162:165], v[58:61]
	v_mfma_f32_16x16x32_bf16 v[54:57], v[130:133], v[184:187], v[54:57]
	v_mfma_f32_16x16x32_bf16 v[50:53], v[138:141], v[184:187], v[50:53]
	v_mfma_f32_16x16x32_bf16 v[46:49], v[130:133], v[214:217], v[46:49]
	v_mfma_f32_16x16x32_bf16 v[42:45], v[138:141], v[214:217], v[42:45]
	v_mfma_f32_16x16x32_bf16 v[38:41], v[130:133], v[222:225], v[38:41]
	v_mfma_f32_16x16x32_bf16 v[34:37], v[138:141], v[222:225], v[34:37]
	v_mfma_f32_16x16x32_bf16 v[62:65], v[134:137], v[180:183], v[62:65]
	v_mfma_f32_16x16x32_bf16 v[58:61], v[142:145], v[180:183], v[58:61]
	v_mfma_f32_16x16x32_bf16 v[54:57], v[134:137], v[210:213], v[54:57]
	v_mfma_f32_16x16x32_bf16 v[50:53], v[142:145], v[210:213], v[50:53]
	v_mfma_f32_16x16x32_bf16 v[46:49], v[134:137], v[218:221], v[46:49]
	v_mfma_f32_16x16x32_bf16 v[42:45], v[142:145], v[218:221], v[42:45]
	v_mfma_f32_16x16x32_bf16 v[38:41], v[134:137], v[226:229], v[38:41]
	v_mfma_f32_16x16x32_bf16 v[34:37], v[142:145], v[226:229], v[34:37]
	s_setprio 0
	s_setprio 1
	v_mfma_f32_16x16x32_bf16 v[30:33], v[146:149], v[162:165], v[30:33]
	v_mfma_f32_16x16x32_bf16 v[26:29], v[154:157], v[162:165], v[26:29]
	v_mfma_f32_16x16x32_bf16 v[22:25], v[146:149], v[184:187], v[22:25]
	v_mfma_f32_16x16x32_bf16 v[18:21], v[154:157], v[184:187], v[18:21]
	v_mfma_f32_16x16x32_bf16 v[14:17], v[146:149], v[214:217], v[14:17]
	v_mfma_f32_16x16x32_bf16 v[10:13], v[154:157], v[214:217], v[10:13]
	v_mfma_f32_16x16x32_bf16 v[6:9], v[146:149], v[222:225], v[6:9]
	v_mfma_f32_16x16x32_bf16 v[2:5], v[154:157], v[222:225], v[2:5]
	v_mfma_f32_16x16x32_bf16 v[30:33], v[150:153], v[180:183], v[30:33]
	v_mfma_f32_16x16x32_bf16 v[26:29], v[158:161], v[180:183], v[26:29]
	v_mfma_f32_16x16x32_bf16 v[22:25], v[150:153], v[210:213], v[22:25]
	v_mfma_f32_16x16x32_bf16 v[18:21], v[158:161], v[210:213], v[18:21]
	v_mfma_f32_16x16x32_bf16 v[14:17], v[150:153], v[218:221], v[14:17]
	v_mfma_f32_16x16x32_bf16 v[10:13], v[158:161], v[218:221], v[10:13]
	v_mfma_f32_16x16x32_bf16 v[6:9], v[150:153], v[226:229], v[6:9]
	v_mfma_f32_16x16x32_bf16 v[2:5], v[158:161], v[226:229], v[2:5]
	s_setprio 0
	s_add_i32 s71, s71, 2
	s_add_u32 s54, s54, 0x100
	s_addc_u32 s55, s55, 0
	s_add_u32 s7, s7, 0x100
	s_addc_u32 s47, s47, 0
	s_cmp_gt_u32 s71, 13
	s_barrier
	s_cbranch_scc0 .LBB0_759
	s_and_b64 vcc, exec, s[42:43]
	s_cbranch_vccz .LBB0_762
	s_barrier

; #define PG8_STAGE(bufoff, gbase, voff) do { _Pragma("unroll") for (int _i = 0; _i < 2; ++_i) \
;         __builtin_amdgcn_global_load_lds((const unsigned*)((const char*)(gbase) + (voff)[_i]), (LAS unsigned*)(lds + (bufoff) + ldsw + _i * 8192), 16, 0, 0); } while (0)
; #define PG8_LDA(dst, b, h) do { _Pragma("unroll") for (int m = 0; m < 4; ++m) _Pragma("unroll") for (int k = 0; k < 2; ++k) dst[m][k] = *(const LAS bf16x8*)(lds + PG8_SA(b, h) + aoff + m * 2048 + k * 1024); } while (0)
; #define PG8_LDB(dst, b, h) do { _Pragma("unroll") for (int n = 0; n < 2; ++n) _Pragma("unroll") for (int k = 0; k < 2; ++k) dst[n][k] = *(const LAS bf16x8*)(lds + PG8_SB(b, h) + boff + n * 2048 + k * 1024); } while (0)
; #define PG8_MMA(ai, bj, At, Bt) do { __builtin_amdgcn_s_setprio(1); _Pragma("unroll") for (int m = 0; m < 4; ++m) _Pragma("unroll") for (int n = 0; n < 2; ++n) _Pragma("unroll") for (int k = 0; k < 2; ++k) \
;         acc[ai][bj][m][n] = __builtin_amdgcn_mfma_f32_16x16x32_bf16(Bt[n][k], At[m][k], acc[ai][bj][m][n], 0, 0, 0); __builtin_amdgcn_s_setprio(0); } while (0)
; #define PG8_WAIT_V(n) asm volatile("s_waitcnt vmcnt(" #n ")" ::: "memory")
; #define PG8_WAIT_L(n) asm volatile("s_waitcnt lgkmcnt(" #n ")" ::: "memory")
; #define PG8_BAR __builtin_amdgcn_s_barrier()
; #define PG8_SCHED __builtin_amdgcn_sched_barrier(0)
; template <class Epi, class Sched>
; __device__ __forceinline__ void gemm_phase(LAS unsigned char* lds, const int K, const Sched& S, const Epi& E) {
;     ...
;             if (last) E.prefetch(lds, cur, wid, lane);
;             const char* a1 = cA + (size_t)(t + 1) * kstep;
;             const char* a2 = last ? nA : cA + (size_t)(t + 2) * kstep; const char* b2 = last ? nB : cB + (size_t)(t + 2) * kstep;
;             const char* a3 = a2 + kstep; const char* b3 = b2 + kstep;
;             PG8_LDB(B0, 0, 0); PG8_LDB(B1, 0, 1); PG8_SCHED; PG8_LDA(At, 0, 0); PG8_STAGE(PG8_SA(1, 1), a1 + hstep, voffA);
;             PG8_WAIT_V(8); PG8_WAIT_L(0); PG8_BAR; PG8_MMA(0, 0, At, B0); PG8_MMA(0, 1, At, B1); PG8_BAR; PG8_SCHED;
;             PG8_LDA(At, 0, 1); PG8_STAGE(PG8_SB(0, 0), b2, voffB); PG8_STAGE(PG8_SB(0, 1), b2 + hstep, voffB); PG8_STAGE(PG8_SA(0, 0), a2, voffA);
;             PG8_WAIT_V(8); PG8_WAIT_L(0); PG8_BAR; PG8_MMA(1, 0, At, B0); PG8_MMA(1, 1, At, B1); PG8_BAR; PG8_SCHED;
.LBB0_864:
	ds_read_b128 v[130:133], v190
	ds_read_b128 v[134:137], v191
	ds_read_b128 v[138:141], v192
	ds_read_b128 v[142:145], v193
	ds_read_b128 v[146:149], v194
	ds_read_b128 v[150:153], v195
	ds_read_b128 v[154:157], v196
	ds_read_b128 v[158:161], v197
	s_add_u32 s52, s50, 0xfffc0080
	s_addc_u32 s53, s51, -1
	s_cmp_eq_u32 s71, 12
	s_cselect_b32 s55, s45, s53
	s_cselect_b32 s54, s44, s52
	s_cselect_b32 s53, s47, s49
	s_cselect_b32 s52, s46, s43
	s_mov_b32 m0, s65
	v_lshl_add_u64 v[182:183], s[50:51], 0, v[170:171]
	ds_read_b128 v[174:177], v188
	ds_read_b128 v[178:181], v188 offset:1024
	ds_read_b128 v[208:211], v188 offset:2048
	ds_read_b128 v[212:215], v188 offset:3072
	ds_read_b128 v[216:219], v188 offset:4096
	ds_read_b128 v[220:223], v188 offset:5120
	ds_read_b128 v[224:227], v188 offset:6144
	ds_read_b128 v[228:231], v188 offset:7168
	global_load_lds_dwordx4 v[182:183], off
	v_lshl_add_u64 v[182:183], s[50:51], 0, v[172:173]
	s_mov_b32 m0, s66
	s_nop 0
	global_load_lds_dwordx4 v[182:183], off
	s_waitcnt vmcnt(8)
	s_waitcnt lgkmcnt(0)
	s_barrier
	s_setprio 1
	s_waitcnt lgkmcnt(0)
	v_mfma_f32_16x16x32_bf16 v[126:129], v[130:133], v[174:177], v[126:129]
	v_mfma_f32_16x16x32_bf16 v[122:125], v[138:141], v[174:177], v[122:125]
	v_mfma_f32_16x16x32_bf16 v[110:113], v[130:133], v[208:211], v[110:113]
	v_mfma_f32_16x16x32_bf16 v[106:109], v[138:141], v[208:211], v[106:109]
	v_mfma_f32_16x16x32_bf16 v[94:97], v[130:133], v[216:219], v[94:97]
	v_mfma_f32_16x16x32_bf16 v[90:93], v[138:141], v[216:219], v[90:93]
	v_mfma_f32_16x16x32_bf16 v[78:81], v[130:133], v[224:227], v[78:81]
	v_mfma_f32_16x16x32_bf16 v[74:77], v[138:141], v[224:227], v[74:77]
	v_mfma_f32_16x16x32_bf16 v[126:129], v[134:137], v[178:181], v[126:129]
	v_mfma_f32_16x16x32_bf16 v[122:125], v[142:145], v[178:181], v[122:125]
	v_mfma_f32_16x16x32_bf16 v[110:113], v[134:137], v[212:215], v[110:113]
	v_mfma_f32_16x16x32_bf16 v[106:109], v[142:145], v[212:215], v[106:109]
	v_mfma_f32_16x16x32_bf16 v[94:97], v[134:137], v[220:223], v[94:97]
	v_mfma_f32_16x16x32_bf16 v[90:93], v[142:145], v[220:223], v[90:93]
	v_mfma_f32_16x16x32_bf16 v[78:81], v[134:137], v[228:231], v[78:81]
	v_mfma_f32_16x16x32_bf16 v[74:77], v[142:145], v[228:231], v[74:77]
	s_setprio 0
	s_setprio 1
	v_mfma_f32_16x16x32_bf16 v[118:121], v[146:149], v[174:177], v[118:121]
	v_mfma_f32_16x16x32_bf16 v[114:117], v[154:157], v[174:177], v[114:117]
	v_mfma_f32_16x16x32_bf16 v[102:105], v[146:149], v[208:211], v[102:105]
	v_mfma_f32_16x16x32_bf16 v[98:101], v[154:157], v[208:211], v[98:101]
	v_mfma_f32_16x16x32_bf16 v[86:89], v[146:149], v[216:219], v[86:89]
	v_mfma_f32_16x16x32_bf16 v[82:85], v[154:157], v[216:219], v[82:85]
	v_mfma_f32_16x16x32_bf16 v[70:73], v[146:149], v[224:227], v[70:73]
	v_mfma_f32_16x16x32_bf16 v[66:69], v[154:157], v[224:227], v[66:69]
	v_mfma_f32_16x16x32_bf16 v[118:121], v[150:153], v[178:181], v[118:121]
	v_mfma_f32_16x16x32_bf16 v[114:117], v[158:161], v[178:181], v[114:117]
	v_mfma_f32_16x16x32_bf16 v[102:105], v[150:153], v[212:215], v[102:105]
	v_mfma_f32_16x16x32_bf16 v[98:101], v[158:161], v[212:215], v[98:101]
	v_mfma_f32_16x16x32_bf16 v[86:89], v[150:153], v[220:223], v[86:89]
	v_mfma_f32_16x16x32_bf16 v[82:85], v[158:161], v[220:223], v[82:85]
	v_mfma_f32_16x16x32_bf16 v[70:73], v[150:153], v[228:231], v[70:73]
	v_mfma_f32_16x16x32_bf16 v[66:69], v[158:161], v[228:231], v[66:69]
	s_setprio 0
	s_barrier
	s_mov_b32 m0, s34
	v_lshl_add_u64 v[182:183], s[52:53], 0, v[164:165]
	s_add_u32 s72, s52, 0x40000
	ds_read_b128 v[174:177], v188 offset:16384
	ds_read_b128 v[178:181], v188 offset:17408
	ds_read_b128 v[208:211], v188 offset:18432
	ds_read_b128 v[212:215], v188 offset:19456
	ds_read_b128 v[216:219], v188 offset:20480
	ds_read_b128 v[220:223], v188 offset:21504
	ds_read_b128 v[224:227], v188 offset:22528
	ds_read_b128 v[228:231], v188 offset:23552
	global_load_lds_dwordx4 v[182:183], off
	v_lshl_add_u64 v[232:233], s[52:53], 0, v[168:169]
	s_mov_b32 m0, s35
	s_addc_u32 s73, s53, 0
	global_load_lds_dwordx4 v[232:233], off
	v_lshl_add_u64 v[234:235], s[72:73], 0, v[164:165]
	s_mov_b32 m0, s36
	v_lshl_add_u64 v[236:237], s[54:55], 0, v[166:167]
	global_load_lds_dwordx4 v[234:235], off
	v_lshl_add_u64 v[234:235], s[72:73], 0, v[168:169]
	s_mov_b32 m0, s37
	s_nop 0
	global_load_lds_dwordx4 v[234:235], off
	v_lshl_add_u64 v[234:235], s[54:55], 0, v[162:163]
	s_mov_b32 m0, s33
	s_nop 0
	global_load_lds_dwordx4 v[234:235], off
	s_mov_b32 m0, s38
	s_nop 0
	global_load_lds_dwordx4 v[236:237], off
	s_waitcnt vmcnt(8)
	s_waitcnt lgkmcnt(0)
	s_barrier
; #define PG8_STAGE(bufoff, gbase, voff) do { _Pragma("unroll") for (int _i = 0; _i < 2; ++_i) \
;         __builtin_amdgcn_global_load_lds((const unsigned*)((const char*)(gbase) + (voff)[_i]), (LAS unsigned*)(lds + (bufoff) + ldsw + _i * 8192), 16, 0, 0); } while (0)
; #define PG8_LDA(dst, b, h) do { _Pragma("unroll") for (int m = 0; m < 4; ++m) _Pragma("unroll") for (int k = 0; k < 2; ++k) dst[m][k] = *(const LAS bf16x8*)(lds + PG8_SA(b, h) + aoff + m * 2048 + k * 1024); } while (0)
; #define PG8_LDB(dst, b, h) do { _Pragma("unroll") for (int n = 0; n < 2; ++n) _Pragma("unroll") for (int k = 0; k < 2; ++k) dst[n][k] = *(const LAS bf16x8*)(lds + PG8_SB(b, h) + boff + n * 2048 + k * 1024); } while (0)
; #define PG8_MMA(ai, bj, At, Bt) do { __builtin_amdgcn_s_setprio(1); _Pragma("unroll") for (int m = 0; m < 4; ++m) _Pragma("unroll") for (int n = 0; n < 2; ++n) _Pragma("unroll") for (int k = 0; k < 2; ++k) \
;         acc[ai][bj][m][n] = __builtin_amdgcn_mfma_f32_16x16x32_bf16(Bt[n][k], At[m][k], acc[ai][bj][m][n], 0, 0, 0); __builtin_amdgcn_s_setprio(0); } while (0)
; #define PG8_WAIT_V(n) asm volatile("s_waitcnt vmcnt(" #n ")" ::: "memory")
; #define PG8_WAIT_L(n) asm volatile("s_waitcnt lgkmcnt(" #n ")" ::: "memory")
; #define PG8_BAR __builtin_amdgcn_s_barrier()
; #define PG8_SCHED __builtin_amdgcn_sched_barrier(0)
; template <class Epi, class Sched>
; __device__ __forceinline__ void gemm_phase(LAS unsigned char* lds, const int K, const Sched& S, const Epi& E) {
;     ...
;             PG8_WAIT_V(8); PG8_WAIT_L(0); PG8_BAR; PG8_MMA(1, 0, At, B0); PG8_MMA(1, 1, At, B1); PG8_BAR; PG8_SCHED;
;             PG8_LDB(B0, 1, 0); PG8_LDB(B1, 1, 1); PG8_SCHED; PG8_LDA(At, 1, 0); PG8_STAGE(PG8_SA(0, 1), a2 + hstep, voffA);
;             PG8_WAIT_V(8); PG8_WAIT_L(0); PG8_BAR; PG8_MMA(0, 0, At, B0); PG8_MMA(0, 1, At, B1); PG8_BAR; PG8_SCHED;
	s_setprio 1
	s_waitcnt lgkmcnt(0)
	v_mfma_f32_16x16x32_bf16 v[62:65], v[130:133], v[174:177], v[62:65]
	v_mfma_f32_16x16x32_bf16 v[58:61], v[138:141], v[174:177], v[58:61]
	v_mfma_f32_16x16x32_bf16 v[46:49], v[130:133], v[208:211], v[46:49]
	v_mfma_f32_16x16x32_bf16 v[42:45], v[138:141], v[208:211], v[42:45]
	v_mfma_f32_16x16x32_bf16 v[30:33], v[130:133], v[216:219], v[30:33]
	v_mfma_f32_16x16x32_bf16 v[26:29], v[138:141], v[216:219], v[26:29]
	v_mfma_f32_16x16x32_bf16 v[14:17], v[130:133], v[224:227], v[14:17]
	v_mfma_f32_16x16x32_bf16 v[10:13], v[138:141], v[224:227], v[10:13]
	v_mfma_f32_16x16x32_bf16 v[62:65], v[134:137], v[178:181], v[62:65]
	v_mfma_f32_16x16x32_bf16 v[58:61], v[142:145], v[178:181], v[58:61]
	v_mfma_f32_16x16x32_bf16 v[46:49], v[134:137], v[212:215], v[46:49]
	v_mfma_f32_16x16x32_bf16 v[42:45], v[142:145], v[212:215], v[42:45]
	v_mfma_f32_16x16x32_bf16 v[30:33], v[134:137], v[220:223], v[30:33]
	v_mfma_f32_16x16x32_bf16 v[26:29], v[142:145], v[220:223], v[26:29]
	v_mfma_f32_16x16x32_bf16 v[14:17], v[134:137], v[228:231], v[14:17]
	v_mfma_f32_16x16x32_bf16 v[10:13], v[142:145], v[228:231], v[10:13]
	s_setprio 0
	s_setprio 1
	v_mfma_f32_16x16x32_bf16 v[54:57], v[146:149], v[174:177], v[54:57]
	v_mfma_f32_16x16x32_bf16 v[50:53], v[154:157], v[174:177], v[50:53]
	v_mfma_f32_16x16x32_bf16 v[38:41], v[146:149], v[208:211], v[38:41]
	v_mfma_f32_16x16x32_bf16 v[34:37], v[154:157], v[208:211], v[34:37]
	v_mfma_f32_16x16x32_bf16 v[22:25], v[146:149], v[216:219], v[22:25]
	v_mfma_f32_16x16x32_bf16 v[18:21], v[154:157], v[216:219], v[18:21]
	v_mfma_f32_16x16x32_bf16 v[6:9], v[146:149], v[224:227], v[6:9]
	v_mfma_f32_16x16x32_bf16 v[2:5], v[154:157], v[224:227], v[2:5]
	v_mfma_f32_16x16x32_bf16 v[54:57], v[150:153], v[178:181], v[54:57]
	v_mfma_f32_16x16x32_bf16 v[50:53], v[158:161], v[178:181], v[50:53]
	v_mfma_f32_16x16x32_bf16 v[38:41], v[150:153], v[212:215], v[38:41]
	v_mfma_f32_16x16x32_bf16 v[34:37], v[158:161], v[212:215], v[34:37]
	v_mfma_f32_16x16x32_bf16 v[22:25], v[150:153], v[220:223], v[22:25]
	v_mfma_f32_16x16x32_bf16 v[18:21], v[158:161], v[220:223], v[18:21]
	v_mfma_f32_16x16x32_bf16 v[6:9], v[150:153], v[228:231], v[6:9]
	v_mfma_f32_16x16x32_bf16 v[2:5], v[158:161], v[228:231], v[2:5]
	s_setprio 0
	s_barrier
	ds_read_b128 v[130:133], v198
	ds_read_b128 v[134:137], v199
	ds_read_b128 v[138:141], v200
	ds_read_b128 v[142:145], v201
	ds_read_b128 v[146:149], v202
	ds_read_b128 v[150:153], v203
	ds_read_b128 v[154:157], v204
	ds_read_b128 v[158:161], v205
	s_add_u32 s54, s54, 0x40000
	s_addc_u32 s55, s55, 0
	s_mov_b32 m0, s39
	v_lshl_add_u64 v[240:241], s[54:55], 0, v[162:163]
	ds_read_b128 v[174:177], v188 offset:32768
	ds_read_b128 v[178:181], v188 offset:33792
	ds_read_b128 v[208:211], v188 offset:34816
	ds_read_b128 v[212:215], v188 offset:35840
	ds_read_b128 v[216:219], v188 offset:36864
	ds_read_b128 v[220:223], v188 offset:37888
	ds_read_b128 v[224:227], v188 offset:38912
	ds_read_b128 v[228:231], v188 offset:39936
	global_load_lds_dwordx4 v[240:241], off
	v_lshl_add_u64 v[240:241], s[54:55], 0, v[166:167]
	s_mov_b32 m0, s56
	s_nop 0
	global_load_lds_dwordx4 v[240:241], off
	s_waitcnt vmcnt(8)
	s_waitcnt lgkmcnt(0)
	s_barrier
	s_setprio 1
	s_waitcnt lgkmcnt(0)
	v_mfma_f32_16x16x32_bf16 v[126:129], v[130:133], v[174:177], v[126:129]
	v_mfma_f32_16x16x32_bf16 v[122:125], v[138:141], v[174:177], v[122:125]
	v_mfma_f32_16x16x32_bf16 v[110:113], v[130:133], v[208:211], v[110:113]
	v_mfma_f32_16x16x32_bf16 v[106:109], v[138:141], v[208:211], v[106:109]
	v_mfma_f32_16x16x32_bf16 v[94:97], v[130:133], v[216:219], v[94:97]
	v_mfma_f32_16x16x32_bf16 v[90:93], v[138:141], v[216:219], v[90:93]
	v_mfma_f32_16x16x32_bf16 v[78:81], v[130:133], v[224:227], v[78:81]
	v_mfma_f32_16x16x32_bf16 v[74:77], v[138:141], v[224:227], v[74:77]
	v_mfma_f32_16x16x32_bf16 v[126:129], v[134:137], v[178:181], v[126:129]
	v_mfma_f32_16x16x32_bf16 v[122:125], v[142:145], v[178:181], v[122:125]
	v_mfma_f32_16x16x32_bf16 v[110:113], v[134:137], v[212:215], v[110:113]
	v_mfma_f32_16x16x32_bf16 v[106:109], v[142:145], v[212:215], v[106:109]
	v_mfma_f32_16x16x32_bf16 v[94:97], v[134:137], v[220:223], v[94:97]
	v_mfma_f32_16x16x32_bf16 v[90:93], v[142:145], v[220:223], v[90:93]
	v_mfma_f32_16x16x32_bf16 v[78:81], v[134:137], v[228:231], v[78:81]
	v_mfma_f32_16x16x32_bf16 v[74:77], v[142:145], v[228:231], v[74:77]
	s_setprio 0
	s_setprio 1
	v_mfma_f32_16x16x32_bf16 v[118:121], v[146:149], v[174:177], v[118:121]
	v_mfma_f32_16x16x32_bf16 v[114:117], v[154:157], v[174:177], v[114:117]
	v_mfma_f32_16x16x32_bf16 v[102:105], v[146:149], v[208:211], v[102:105]
	v_mfma_f32_16x16x32_bf16 v[98:101], v[154:157], v[208:211], v[98:101]
	v_mfma_f32_16x16x32_bf16 v[86:89], v[146:149], v[216:219], v[86:89]
	v_mfma_f32_16x16x32_bf16 v[82:85], v[154:157], v[216:219], v[82:85]
	v_mfma_f32_16x16x32_bf16 v[70:73], v[146:149], v[224:227], v[70:73]
	v_mfma_f32_16x16x32_bf16 v[66:69], v[154:157], v[224:227], v[66:69]
	v_mfma_f32_16x16x32_bf16 v[118:121], v[150:153], v[178:181], v[118:121]
	v_mfma_f32_16x16x32_bf16 v[114:117], v[158:161], v[178:181], v[114:117]
	v_mfma_f32_16x16x32_bf16 v[102:105], v[150:153], v[212:215], v[102:105]
	v_mfma_f32_16x16x32_bf16 v[98:101], v[158:161], v[212:215], v[98:101]
	v_mfma_f32_16x16x32_bf16 v[86:89], v[150:153], v[220:223], v[86:89]
	v_mfma_f32_16x16x32_bf16 v[82:85], v[158:161], v[220:223], v[82:85]
	v_mfma_f32_16x16x32_bf16 v[70:73], v[150:153], v[228:231], v[70:73]
	v_mfma_f32_16x16x32_bf16 v[66:69], v[158:161], v[228:231], v[66:69]
	s_setprio 0
	s_barrier
; #define PG8_STAGE(bufoff, gbase, voff) do { _Pragma("unroll") for (int _i = 0; _i < 2; ++_i) \
;         __builtin_amdgcn_global_load_lds((const unsigned*)((const char*)(gbase) + (voff)[_i]), (LAS unsigned*)(lds + (bufoff) + ldsw + _i * 8192), 16, 0, 0); } while (0)
; #define PG8_LDA(dst, b, h) do { _Pragma("unroll") for (int m = 0; m < 4; ++m) _Pragma("unroll") for (int k = 0; k < 2; ++k) dst[m][k] = *(const LAS bf16x8*)(lds + PG8_SA(b, h) + aoff + m * 2048 + k * 1024); } while (0)
; #define PG8_MMA(ai, bj, At, Bt) do { __builtin_amdgcn_s_setprio(1); _Pragma("unroll") for (int m = 0; m < 4; ++m) _Pragma("unroll") for (int n = 0; n < 2; ++n) _Pragma("unroll") for (int k = 0; k < 2; ++k) \
;         acc[ai][bj][m][n] = __builtin_amdgcn_mfma_f32_16x16x32_bf16(Bt[n][k], At[m][k], acc[ai][bj][m][n], 0, 0, 0); __builtin_amdgcn_s_setprio(0); } while (0)
; #define PG8_WAIT_V(n) asm volatile("s_waitcnt vmcnt(" #n ")" ::: "memory")
; #define PG8_WAIT_L(n) asm volatile("s_waitcnt lgkmcnt(" #n ")" ::: "memory")
; #define PG8_BAR __builtin_amdgcn_s_barrier()
; #define PG8_SCHED __builtin_amdgcn_sched_barrier(0)
; template <class Epi, class Sched>
; __device__ __forceinline__ void gemm_phase(LAS unsigned char* lds, const int K, const Sched& S, const Epi& E) {
;     ...
;             PG8_LDA(At, 1, 1); PG8_STAGE(PG8_SB(1, 0), b3, voffB); PG8_STAGE(PG8_SB(1, 1), b3 + hstep, voffB); PG8_STAGE(PG8_SA(1, 0), a3, voffA);
;             PG8_WAIT_V(8); PG8_WAIT_L(0); PG8_BAR; PG8_MMA(1, 0, At, B0); PG8_MMA(1, 1, At, B1); PG8_BAR; PG8_SCHED;
;         }
	s_mov_b32 m0, s58
	v_lshl_add_u64 v[182:183], v[182:183], 0, s[24:25]
	s_add_u32 s52, s52, 0x40080
	ds_read_b128 v[174:177], v188 offset:49152
	ds_read_b128 v[178:181], v188 offset:50176
	ds_read_b128 v[208:211], v188 offset:51200
	ds_read_b128 v[212:215], v188 offset:52224
	ds_read_b128 v[216:219], v188 offset:53248
	ds_read_b128 v[220:223], v188 offset:54272
	ds_read_b128 v[224:227], v188 offset:55296
	ds_read_b128 v[228:231], v188 offset:56320
	global_load_lds_dwordx4 v[182:183], off
	v_lshl_add_u64 v[182:183], v[232:233], 0, s[24:25]
	s_mov_b32 m0, s59
	s_addc_u32 s53, s53, 0
	global_load_lds_dwordx4 v[182:183], off
	v_lshl_add_u64 v[182:183], s[52:53], 0, v[164:165]
	s_mov_b32 m0, s62
	s_nop 0
	global_load_lds_dwordx4 v[182:183], off
	v_lshl_add_u64 v[182:183], s[52:53], 0, v[168:169]
	s_mov_b32 m0, s63
	s_nop 0
	global_load_lds_dwordx4 v[182:183], off
	v_lshl_add_u64 v[182:183], v[234:235], 0, s[24:25]
	s_mov_b32 m0, s60
	s_nop 0
	global_load_lds_dwordx4 v[182:183], off
	v_lshl_add_u64 v[182:183], v[236:237], 0, s[24:25]
	s_mov_b32 m0, s61
	s_nop 0
	global_load_lds_dwordx4 v[182:183], off
	s_waitcnt vmcnt(8)
	s_waitcnt lgkmcnt(0)
	s_barrier
	s_setprio 1
	s_waitcnt lgkmcnt(0)
	v_mfma_f32_16x16x32_bf16 v[62:65], v[130:133], v[174:177], v[62:65]
	v_mfma_f32_16x16x32_bf16 v[58:61], v[138:141], v[174:177], v[58:61]
	v_mfma_f32_16x16x32_bf16 v[46:49], v[130:133], v[208:211], v[46:49]
	v_mfma_f32_16x16x32_bf16 v[42:45], v[138:141], v[208:211], v[42:45]
	v_mfma_f32_16x16x32_bf16 v[30:33], v[130:133], v[216:219], v[30:33]
	v_mfma_f32_16x16x32_bf16 v[26:29], v[138:141], v[216:219], v[26:29]
	v_mfma_f32_16x16x32_bf16 v[14:17], v[130:133], v[224:227], v[14:17]
	v_mfma_f32_16x16x32_bf16 v[10:13], v[138:141], v[224:227], v[10:13]
	v_mfma_f32_16x16x32_bf16 v[62:65], v[134:137], v[178:181], v[62:65]
	v_mfma_f32_16x16x32_bf16 v[58:61], v[142:145], v[178:181], v[58:61]
	v_mfma_f32_16x16x32_bf16 v[46:49], v[134:137], v[212:215], v[46:49]
	v_mfma_f32_16x16x32_bf16 v[42:45], v[142:145], v[212:215], v[42:45]
	v_mfma_f32_16x16x32_bf16 v[30:33], v[134:137], v[220:223], v[30:33]
	v_mfma_f32_16x16x32_bf16 v[26:29], v[142:145], v[220:223], v[26:29]
	v_mfma_f32_16x16x32_bf16 v[14:17], v[134:137], v[228:231], v[14:17]
	v_mfma_f32_16x16x32_bf16 v[10:13], v[142:145], v[228:231], v[10:13]
	s_setprio 0
	s_setprio 1
	v_mfma_f32_16x16x32_bf16 v[54:57], v[146:149], v[174:177], v[54:57]
	v_mfma_f32_16x16x32_bf16 v[50:53], v[154:157], v[174:177], v[50:53]
	v_mfma_f32_16x16x32_bf16 v[38:41], v[146:149], v[208:211], v[38:41]
	v_mfma_f32_16x16x32_bf16 v[34:37], v[154:157], v[208:211], v[34:37]
	v_mfma_f32_16x16x32_bf16 v[22:25], v[146:149], v[216:219], v[22:25]
	v_mfma_f32_16x16x32_bf16 v[18:21], v[154:157], v[216:219], v[18:21]
	v_mfma_f32_16x16x32_bf16 v[6:9], v[146:149], v[224:227], v[6:9]
	v_mfma_f32_16x16x32_bf16 v[2:5], v[154:157], v[224:227], v[2:5]
	v_mfma_f32_16x16x32_bf16 v[54:57], v[150:153], v[178:181], v[54:57]
	v_mfma_f32_16x16x32_bf16 v[50:53], v[158:161], v[178:181], v[50:53]
	v_mfma_f32_16x16x32_bf16 v[38:41], v[150:153], v[212:215], v[38:41]
	v_mfma_f32_16x16x32_bf16 v[34:37], v[158:161], v[212:215], v[34:37]
	v_mfma_f32_16x16x32_bf16 v[22:25], v[150:153], v[220:223], v[22:25]
	v_mfma_f32_16x16x32_bf16 v[18:21], v[158:161], v[220:223], v[18:21]
	v_mfma_f32_16x16x32_bf16 v[6:9], v[150:153], v[228:231], v[6:9]
	v_mfma_f32_16x16x32_bf16 v[2:5], v[158:161], v[228:231], v[2:5]
	s_setprio 0
	s_add_i32 s71, s71, 2
	s_add_u32 s50, s50, 0x100
	s_addc_u32 s51, s51, 0
	s_add_u32 s43, s43, 0x100
	s_addc_u32 s49, s49, 0
	s_cmp_gt_u32 s71, 13
	s_barrier
	s_cbranch_scc0 .LBB0_864
	s_and_b64 vcc, exec, s[26:27]
	s_cbranch_vccz .LBB0_867
	s_barrier

; #define PG8_STAGE(bufoff, gbase, voff) do { _Pragma("unroll") for (int _i = 0; _i < 2; ++_i) \
;         __builtin_amdgcn_global_load_lds((const unsigned*)((const char*)(gbase) + (voff)[_i]), (LAS unsigned*)(lds + (bufoff) + ldsw + _i * 8192), 16, 0, 0); } while (0)
; #define PG8_LDA(dst, b, h) do { _Pragma("unroll") for (int m = 0; m < 4; ++m) _Pragma("unroll") for (int k = 0; k < 2; ++k) dst[m][k] = *(const LAS bf16x8*)(lds + PG8_SA(b, h) + aoff + m * 2048 + k * 1024); } while (0)
; #define PG8_LDB(dst, b, h) do { _Pragma("unroll") for (int n = 0; n < 2; ++n) _Pragma("unroll") for (int k = 0; k < 2; ++k) dst[n][k] = *(const LAS bf16x8*)(lds + PG8_SB(b, h) + boff + n * 2048 + k * 1024); } while (0)
; #define PG8_MMA(ai, bj, At, Bt) do { __builtin_amdgcn_s_setprio(1); _Pragma("unroll") for (int m = 0; m < 4; ++m) _Pragma("unroll") for (int n = 0; n < 2; ++n) _Pragma("unroll") for (int k = 0; k < 2; ++k) \
;         acc[ai][bj][m][n] = __builtin_amdgcn_mfma_f32_16x16x32_bf16(Bt[n][k], At[m][k], acc[ai][bj][m][n], 0, 0, 0); __builtin_amdgcn_s_setprio(0); } while (0)
; #define PG8_WAIT_V(n) asm volatile("s_waitcnt vmcnt(" #n ")" ::: "memory")
; #define PG8_WAIT_L(n) asm volatile("s_waitcnt lgkmcnt(" #n ")" ::: "memory")
; #define PG8_BAR __builtin_amdgcn_s_barrier()
; #define PG8_SCHED __builtin_amdgcn_sched_barrier(0)
; template <class Epi, class Sched>
; __device__ __forceinline__ void gemm_phase(LAS unsigned char* lds, const int K, const Sched& S, const Epi& E) {
;     ...
;             if (last) E.prefetch(lds, cur, wid, lane);
;             const char* a1 = cA + (size_t)(t + 1) * kstep;
;             const char* a2 = last ? nA : cA + (size_t)(t + 2) * kstep; const char* b2 = last ? nB : cB + (size_t)(t + 2) * kstep;
;             const char* a3 = a2 + kstep; const char* b3 = b2 + kstep;
;             PG8_LDB(B0, 0, 0); PG8_LDB(B1, 0, 1); PG8_SCHED; PG8_LDA(At, 0, 0); PG8_STAGE(PG8_SA(1, 1), a1 + hstep, voffA);
;             PG8_WAIT_V(8); PG8_WAIT_L(0); PG8_BAR; PG8_MMA(0, 0, At, B0); PG8_MMA(0, 1, At, B1); PG8_BAR; PG8_SCHED;
;             PG8_LDA(At, 0, 1); PG8_STAGE(PG8_SB(0, 0), b2, voffB); PG8_STAGE(PG8_SB(0, 1), b2 + hstep, voffB); PG8_STAGE(PG8_SA(0, 0), a2, voffA);
;             PG8_WAIT_V(8); PG8_WAIT_L(0); PG8_BAR; PG8_MMA(1, 0, At, B0); PG8_MMA(1, 1, At, B1); PG8_BAR; PG8_SCHED;
.LBB0_972:
	ds_read_b128 v[168:171], v149
	ds_read_b128 v[172:175], v150
	ds_read_b128 v[176:179], v151
	ds_read_b128 v[180:183], v152
	ds_read_b128 v[184:187], v153
	ds_read_b128 v[188:191], v154
	ds_read_b128 v[192:195], v155
	ds_read_b128 v[196:199], v156
	s_add_u32 s44, s6, 0xfffc0080
	s_addc_u32 s45, s7, -1
	s_and_b64 s[42:43], s[42:43], exec
	s_cselect_b32 s45, s25, s45
	s_cselect_b32 s44, s24, s44
	s_cselect_b32 s43, s27, s41
	s_cselect_b32 s42, s26, s23
	s_mov_b32 m0, s54
	v_lshl_add_u64 v[232:233], s[6:7], 0, v[140:141]
	ds_read_b128 v[200:203], v146
	ds_read_b128 v[204:207], v146 offset:1024
	ds_read_b128 v[208:211], v146 offset:2048
	ds_read_b128 v[212:215], v146 offset:3072
	ds_read_b128 v[216:219], v146 offset:4096
	ds_read_b128 v[220:223], v146 offset:5120
	ds_read_b128 v[224:227], v146 offset:6144
	ds_read_b128 v[228:231], v146 offset:7168
	global_load_lds_dwordx4 v[232:233], off
	v_lshl_add_u64 v[232:233], s[6:7], 0, v[142:143]
	s_mov_b32 m0, s55
	s_nop 0
	global_load_lds_dwordx4 v[232:233], off
	s_waitcnt vmcnt(8)
	s_waitcnt lgkmcnt(0)
	s_barrier
	s_setprio 1
	s_waitcnt lgkmcnt(0)
	v_mfma_f32_16x16x32_bf16 v[126:129], v[168:171], v[200:203], v[126:129]
	v_mfma_f32_16x16x32_bf16 v[122:125], v[176:179], v[200:203], v[122:125]
	v_mfma_f32_16x16x32_bf16 v[110:113], v[168:171], v[208:211], v[110:113]
	v_mfma_f32_16x16x32_bf16 v[106:109], v[176:179], v[208:211], v[106:109]
	v_mfma_f32_16x16x32_bf16 v[94:97], v[168:171], v[216:219], v[94:97]
	v_mfma_f32_16x16x32_bf16 v[90:93], v[176:179], v[216:219], v[90:93]
	v_mfma_f32_16x16x32_bf16 v[78:81], v[168:171], v[224:227], v[78:81]
	v_mfma_f32_16x16x32_bf16 v[74:77], v[176:179], v[224:227], v[74:77]
	v_mfma_f32_16x16x32_bf16 v[126:129], v[172:175], v[204:207], v[126:129]
	v_mfma_f32_16x16x32_bf16 v[122:125], v[180:183], v[204:207], v[122:125]
	v_mfma_f32_16x16x32_bf16 v[110:113], v[172:175], v[212:215], v[110:113]
	v_mfma_f32_16x16x32_bf16 v[106:109], v[180:183], v[212:215], v[106:109]
	v_mfma_f32_16x16x32_bf16 v[94:97], v[172:175], v[220:223], v[94:97]
	v_mfma_f32_16x16x32_bf16 v[90:93], v[180:183], v[220:223], v[90:93]
	v_mfma_f32_16x16x32_bf16 v[78:81], v[172:175], v[228:231], v[78:81]
	v_mfma_f32_16x16x32_bf16 v[74:77], v[180:183], v[228:231], v[74:77]
	s_setprio 0
	s_setprio 1
	v_mfma_f32_16x16x32_bf16 v[118:121], v[184:187], v[200:203], v[118:121]
	v_mfma_f32_16x16x32_bf16 v[114:117], v[192:195], v[200:203], v[114:117]
	v_mfma_f32_16x16x32_bf16 v[102:105], v[184:187], v[208:211], v[102:105]
	v_mfma_f32_16x16x32_bf16 v[98:101], v[192:195], v[208:211], v[98:101]
	v_mfma_f32_16x16x32_bf16 v[86:89], v[184:187], v[216:219], v[86:89]
	v_mfma_f32_16x16x32_bf16 v[82:85], v[192:195], v[216:219], v[82:85]
	v_mfma_f32_16x16x32_bf16 v[70:73], v[184:187], v[224:227], v[70:73]
	v_mfma_f32_16x16x32_bf16 v[66:69], v[192:195], v[224:227], v[66:69]
	v_mfma_f32_16x16x32_bf16 v[118:121], v[188:191], v[204:207], v[118:121]
	v_mfma_f32_16x16x32_bf16 v[114:117], v[196:199], v[204:207], v[114:117]
	v_mfma_f32_16x16x32_bf16 v[102:105], v[188:191], v[212:215], v[102:105]
	v_mfma_f32_16x16x32_bf16 v[98:101], v[196:199], v[212:215], v[98:101]
	v_mfma_f32_16x16x32_bf16 v[86:89], v[188:191], v[220:223], v[86:89]
	v_mfma_f32_16x16x32_bf16 v[82:85], v[196:199], v[220:223], v[82:85]
	v_mfma_f32_16x16x32_bf16 v[70:73], v[188:191], v[228:231], v[70:73]
	v_mfma_f32_16x16x32_bf16 v[66:69], v[196:199], v[228:231], v[66:69]
	s_setprio 0
	s_barrier
	s_mov_b32 m0, s34
	v_lshl_add_u64 v[232:233], s[42:43], 0, v[132:133]
	s_add_u32 s62, s42, 0x40000
	ds_read_b128 v[200:203], v146 offset:16384
	ds_read_b128 v[204:207], v146 offset:17408
	ds_read_b128 v[208:211], v146 offset:18432
	ds_read_b128 v[212:215], v146 offset:19456
	ds_read_b128 v[216:219], v146 offset:20480
	ds_read_b128 v[220:223], v146 offset:21504
	ds_read_b128 v[224:227], v146 offset:22528
	ds_read_b128 v[228:231], v146 offset:23552
	global_load_lds_dwordx4 v[232:233], off
	v_lshl_add_u64 v[234:235], s[42:43], 0, v[136:137]
	s_mov_b32 m0, s35
	s_addc_u32 s63, s43, 0
	global_load_lds_dwordx4 v[234:235], off
	v_lshl_add_u64 v[236:237], s[62:63], 0, v[132:133]
	s_mov_b32 m0, s36
	v_lshl_add_u64 v[240:241], s[44:45], 0, v[134:135]
	global_load_lds_dwordx4 v[236:237], off
	v_lshl_add_u64 v[236:237], s[62:63], 0, v[136:137]
	s_mov_b32 m0, s37
	s_nop 0
	global_load_lds_dwordx4 v[236:237], off
	v_lshl_add_u64 v[236:237], s[44:45], 0, v[130:131]
	s_mov_b32 m0, s33
	s_nop 0
	global_load_lds_dwordx4 v[236:237], off
	s_mov_b32 m0, s38
	s_nop 0
	global_load_lds_dwordx4 v[240:241], off
	s_waitcnt vmcnt(8)
	s_waitcnt lgkmcnt(0)
	s_barrier
; #define PG8_STAGE(bufoff, gbase, voff) do { _Pragma("unroll") for (int _i = 0; _i < 2; ++_i) \
;         __builtin_amdgcn_global_load_lds((const unsigned*)((const char*)(gbase) + (voff)[_i]), (LAS unsigned*)(lds + (bufoff) + ldsw + _i * 8192), 16, 0, 0); } while (0)
; #define PG8_LDA(dst, b, h) do { _Pragma("unroll") for (int m = 0; m < 4; ++m) _Pragma("unroll") for (int k = 0; k < 2; ++k) dst[m][k] = *(const LAS bf16x8*)(lds + PG8_SA(b, h) + aoff + m * 2048 + k * 1024); } while (0)
; #define PG8_LDB(dst, b, h) do { _Pragma("unroll") for (int n = 0; n < 2; ++n) _Pragma("unroll") for (int k = 0; k < 2; ++k) dst[n][k] = *(const LAS bf16x8*)(lds + PG8_SB(b, h) + boff + n * 2048 + k * 1024); } while (0)
; #define PG8_MMA(ai, bj, At, Bt) do { __builtin_amdgcn_s_setprio(1); _Pragma("unroll") for (int m = 0; m < 4; ++m) _Pragma("unroll") for (int n = 0; n < 2; ++n) _Pragma("unroll") for (int k = 0; k < 2; ++k) \
;         acc[ai][bj][m][n] = __builtin_amdgcn_mfma_f32_16x16x32_bf16(Bt[n][k], At[m][k], acc[ai][bj][m][n], 0, 0, 0); __builtin_amdgcn_s_setprio(0); } while (0)
; #define PG8_WAIT_V(n) asm volatile("s_waitcnt vmcnt(" #n ")" ::: "memory")
; #define PG8_WAIT_L(n) asm volatile("s_waitcnt lgkmcnt(" #n ")" ::: "memory")
; #define PG8_BAR __builtin_amdgcn_s_barrier()
; #define PG8_SCHED __builtin_amdgcn_sched_barrier(0)
; template <class Epi, class Sched>
; __device__ __forceinline__ void gemm_phase(LAS unsigned char* lds, const int K, const Sched& S, const Epi& E) {
;     ...
;             PG8_WAIT_V(8); PG8_WAIT_L(0); PG8_BAR; PG8_MMA(1, 0, At, B0); PG8_MMA(1, 1, At, B1); PG8_BAR; PG8_SCHED;
;             PG8_LDB(B0, 1, 0); PG8_LDB(B1, 1, 1); PG8_SCHED; PG8_LDA(At, 1, 0); PG8_STAGE(PG8_SA(0, 1), a2 + hstep, voffA);
;             PG8_WAIT_V(8); PG8_WAIT_L(0); PG8_BAR; PG8_MMA(0, 0, At, B0); PG8_MMA(0, 1, At, B1); PG8_BAR; PG8_SCHED;
	s_setprio 1
	s_waitcnt lgkmcnt(0)
	v_mfma_f32_16x16x32_bf16 v[62:65], v[168:171], v[200:203], v[62:65]
	v_mfma_f32_16x16x32_bf16 v[58:61], v[176:179], v[200:203], v[58:61]
	v_mfma_f32_16x16x32_bf16 v[46:49], v[168:171], v[208:211], v[46:49]
	v_mfma_f32_16x16x32_bf16 v[42:45], v[176:179], v[208:211], v[42:45]
	v_mfma_f32_16x16x32_bf16 v[30:33], v[168:171], v[216:219], v[30:33]
	v_mfma_f32_16x16x32_bf16 v[26:29], v[176:179], v[216:219], v[26:29]
	v_mfma_f32_16x16x32_bf16 v[14:17], v[168:171], v[224:227], v[14:17]
	v_mfma_f32_16x16x32_bf16 v[10:13], v[176:179], v[224:227], v[10:13]
	v_mfma_f32_16x16x32_bf16 v[62:65], v[172:175], v[204:207], v[62:65]
	v_mfma_f32_16x16x32_bf16 v[58:61], v[180:183], v[204:207], v[58:61]
	v_mfma_f32_16x16x32_bf16 v[46:49], v[172:175], v[212:215], v[46:49]
	v_mfma_f32_16x16x32_bf16 v[42:45], v[180:183], v[212:215], v[42:45]
	v_mfma_f32_16x16x32_bf16 v[30:33], v[172:175], v[220:223], v[30:33]
	v_mfma_f32_16x16x32_bf16 v[26:29], v[180:183], v[220:223], v[26:29]
	v_mfma_f32_16x16x32_bf16 v[14:17], v[172:175], v[228:231], v[14:17]
	v_mfma_f32_16x16x32_bf16 v[10:13], v[180:183], v[228:231], v[10:13]
	s_setprio 0
	s_setprio 1
	v_mfma_f32_16x16x32_bf16 v[54:57], v[184:187], v[200:203], v[54:57]
	v_mfma_f32_16x16x32_bf16 v[50:53], v[192:195], v[200:203], v[50:53]
	v_mfma_f32_16x16x32_bf16 v[38:41], v[184:187], v[208:211], v[38:41]
	v_mfma_f32_16x16x32_bf16 v[34:37], v[192:195], v[208:211], v[34:37]
	v_mfma_f32_16x16x32_bf16 v[22:25], v[184:187], v[216:219], v[22:25]
	v_mfma_f32_16x16x32_bf16 v[18:21], v[192:195], v[216:219], v[18:21]
	v_mfma_f32_16x16x32_bf16 v[6:9], v[184:187], v[224:227], v[6:9]
	v_mfma_f32_16x16x32_bf16 v[2:5], v[192:195], v[224:227], v[2:5]
	v_mfma_f32_16x16x32_bf16 v[54:57], v[188:191], v[204:207], v[54:57]
	v_mfma_f32_16x16x32_bf16 v[50:53], v[196:199], v[204:207], v[50:53]
	v_mfma_f32_16x16x32_bf16 v[38:41], v[188:191], v[212:215], v[38:41]
	v_mfma_f32_16x16x32_bf16 v[34:37], v[196:199], v[212:215], v[34:37]
	v_mfma_f32_16x16x32_bf16 v[22:25], v[188:191], v[220:223], v[22:25]
	v_mfma_f32_16x16x32_bf16 v[18:21], v[196:199], v[220:223], v[18:21]
	v_mfma_f32_16x16x32_bf16 v[6:9], v[188:191], v[228:231], v[6:9]
	v_mfma_f32_16x16x32_bf16 v[2:5], v[196:199], v[228:231], v[2:5]
	s_setprio 0
	s_barrier
	ds_read_b128 v[168:171], v157
	ds_read_b128 v[172:175], v158
	ds_read_b128 v[176:179], v159
	ds_read_b128 v[180:183], v160
	ds_read_b128 v[184:187], v161
	ds_read_b128 v[188:191], v162
	ds_read_b128 v[192:195], v163
	ds_read_b128 v[196:199], v164
	s_add_u32 s44, s44, 0x40000
	s_addc_u32 s45, s45, 0
	s_mov_b32 m0, s39
	v_lshl_add_u64 v[242:243], s[44:45], 0, v[130:131]
	ds_read_b128 v[200:203], v146 offset:32768
	ds_read_b128 v[204:207], v146 offset:33792
	ds_read_b128 v[208:211], v146 offset:34816
	ds_read_b128 v[212:215], v146 offset:35840
	ds_read_b128 v[216:219], v146 offset:36864
	ds_read_b128 v[220:223], v146 offset:37888
	ds_read_b128 v[224:227], v146 offset:38912
	ds_read_b128 v[228:231], v146 offset:39936
	global_load_lds_dwordx4 v[242:243], off
	v_lshl_add_u64 v[242:243], s[44:45], 0, v[134:135]
	s_mov_b32 m0, s46
	s_nop 0
	global_load_lds_dwordx4 v[242:243], off
	s_waitcnt vmcnt(8)
	s_waitcnt lgkmcnt(0)
	s_barrier
	s_setprio 1
	s_waitcnt lgkmcnt(0)
	v_mfma_f32_16x16x32_bf16 v[126:129], v[168:171], v[200:203], v[126:129]
	v_mfma_f32_16x16x32_bf16 v[122:125], v[176:179], v[200:203], v[122:125]
	v_mfma_f32_16x16x32_bf16 v[110:113], v[168:171], v[208:211], v[110:113]
	v_mfma_f32_16x16x32_bf16 v[106:109], v[176:179], v[208:211], v[106:109]
	v_mfma_f32_16x16x32_bf16 v[94:97], v[168:171], v[216:219], v[94:97]
	v_mfma_f32_16x16x32_bf16 v[90:93], v[176:179], v[216:219], v[90:93]
	v_mfma_f32_16x16x32_bf16 v[78:81], v[168:171], v[224:227], v[78:81]
	v_mfma_f32_16x16x32_bf16 v[74:77], v[176:179], v[224:227], v[74:77]
	v_mfma_f32_16x16x32_bf16 v[126:129], v[172:175], v[204:207], v[126:129]
	v_mfma_f32_16x16x32_bf16 v[122:125], v[180:183], v[204:207], v[122:125]
	v_mfma_f32_16x16x32_bf16 v[110:113], v[172:175], v[212:215], v[110:113]
	v_mfma_f32_16x16x32_bf16 v[106:109], v[180:183], v[212:215], v[106:109]
	v_mfma_f32_16x16x32_bf16 v[94:97], v[172:175], v[220:223], v[94:97]
	v_mfma_f32_16x16x32_bf16 v[90:93], v[180:183], v[220:223], v[90:93]
	v_mfma_f32_16x16x32_bf16 v[78:81], v[172:175], v[228:231], v[78:81]
	v_mfma_f32_16x16x32_bf16 v[74:77], v[180:183], v[228:231], v[74:77]
	s_setprio 0
	s_setprio 1
	v_mfma_f32_16x16x32_bf16 v[118:121], v[184:187], v[200:203], v[118:121]
	v_mfma_f32_16x16x32_bf16 v[114:117], v[192:195], v[200:203], v[114:117]
	v_mfma_f32_16x16x32_bf16 v[102:105], v[184:187], v[208:211], v[102:105]
	v_mfma_f32_16x16x32_bf16 v[98:101], v[192:195], v[208:211], v[98:101]
	v_mfma_f32_16x16x32_bf16 v[86:89], v[184:187], v[216:219], v[86:89]
	v_mfma_f32_16x16x32_bf16 v[82:85], v[192:195], v[216:219], v[82:85]
	v_mfma_f32_16x16x32_bf16 v[70:73], v[184:187], v[224:227], v[70:73]
	v_mfma_f32_16x16x32_bf16 v[66:69], v[192:195], v[224:227], v[66:69]
	v_mfma_f32_16x16x32_bf16 v[118:121], v[188:191], v[204:207], v[118:121]
	v_mfma_f32_16x16x32_bf16 v[114:117], v[196:199], v[204:207], v[114:117]
	v_mfma_f32_16x16x32_bf16 v[102:105], v[188:191], v[212:215], v[102:105]
	v_mfma_f32_16x16x32_bf16 v[98:101], v[196:199], v[212:215], v[98:101]
	v_mfma_f32_16x16x32_bf16 v[86:89], v[188:191], v[220:223], v[86:89]
	v_mfma_f32_16x16x32_bf16 v[82:85], v[196:199], v[220:223], v[82:85]
	v_mfma_f32_16x16x32_bf16 v[70:73], v[188:191], v[228:231], v[70:73]
	v_mfma_f32_16x16x32_bf16 v[66:69], v[196:199], v[228:231], v[66:69]
	s_setprio 0
	s_barrier
; #define PG8_STAGE(bufoff, gbase, voff) do { _Pragma("unroll") for (int _i = 0; _i < 2; ++_i) \
;         __builtin_amdgcn_global_load_lds((const unsigned*)((const char*)(gbase) + (voff)[_i]), (LAS unsigned*)(lds + (bufoff) + ldsw + _i * 8192), 16, 0, 0); } while (0)
; #define PG8_LDA(dst, b, h) do { _Pragma("unroll") for (int m = 0; m < 4; ++m) _Pragma("unroll") for (int k = 0; k < 2; ++k) dst[m][k] = *(const LAS bf16x8*)(lds + PG8_SA(b, h) + aoff + m * 2048 + k * 1024); } while (0)
; #define PG8_MMA(ai, bj, At, Bt) do { __builtin_amdgcn_s_setprio(1); _Pragma("unroll") for (int m = 0; m < 4; ++m) _Pragma("unroll") for (int n = 0; n < 2; ++n) _Pragma("unroll") for (int k = 0; k < 2; ++k) \
;         acc[ai][bj][m][n] = __builtin_amdgcn_mfma_f32_16x16x32_bf16(Bt[n][k], At[m][k], acc[ai][bj][m][n], 0, 0, 0); __builtin_amdgcn_s_setprio(0); } while (0)
; #define PG8_WAIT_V(n) asm volatile("s_waitcnt vmcnt(" #n ")" ::: "memory")
; #define PG8_WAIT_L(n) asm volatile("s_waitcnt lgkmcnt(" #n ")" ::: "memory")
; #define PG8_BAR __builtin_amdgcn_s_barrier()
; #define PG8_SCHED __builtin_amdgcn_sched_barrier(0)
; template <class Epi, class Sched>
; __device__ __forceinline__ void gemm_phase(LAS unsigned char* lds, const int K, const Sched& S, const Epi& E) {
;     ...
;             PG8_LDA(At, 1, 1); PG8_STAGE(PG8_SB(1, 0), b3, voffB); PG8_STAGE(PG8_SB(1, 1), b3 + hstep, voffB); PG8_STAGE(PG8_SA(1, 0), a3, voffA);
;             PG8_WAIT_V(8); PG8_WAIT_L(0); PG8_BAR; PG8_MMA(1, 0, At, B0); PG8_MMA(1, 1, At, B1); PG8_BAR; PG8_SCHED;
;         }
	s_mov_b32 m0, s48
	v_lshl_add_u64 v[232:233], v[232:233], 0, s[14:15]
	s_add_u32 s42, s42, 0x40080
	ds_read_b128 v[200:203], v146 offset:49152
	ds_read_b128 v[204:207], v146 offset:50176
	ds_read_b128 v[208:211], v146 offset:51200
	ds_read_b128 v[212:215], v146 offset:52224
	ds_read_b128 v[216:219], v146 offset:53248
	ds_read_b128 v[220:223], v146 offset:54272
	ds_read_b128 v[224:227], v146 offset:55296
	ds_read_b128 v[228:231], v146 offset:56320
	global_load_lds_dwordx4 v[232:233], off
	v_lshl_add_u64 v[232:233], v[234:235], 0, s[14:15]
	s_mov_b32 m0, s49
	s_addc_u32 s43, s43, 0
	global_load_lds_dwordx4 v[232:233], off
	v_lshl_add_u64 v[232:233], s[42:43], 0, v[132:133]
	s_mov_b32 m0, s52
	s_nop 0
	global_load_lds_dwordx4 v[232:233], off
	v_lshl_add_u64 v[232:233], s[42:43], 0, v[136:137]
	s_mov_b32 m0, s53
	s_nop 0
	global_load_lds_dwordx4 v[232:233], off
	v_lshl_add_u64 v[232:233], v[236:237], 0, s[14:15]
	s_mov_b32 m0, s50
	s_nop 0
	global_load_lds_dwordx4 v[232:233], off
	v_lshl_add_u64 v[232:233], v[240:241], 0, s[14:15]
	s_mov_b32 m0, s51
	s_nop 0
	global_load_lds_dwordx4 v[232:233], off
	s_waitcnt vmcnt(8)
	s_waitcnt lgkmcnt(0)
	s_barrier
	s_setprio 1
	s_waitcnt lgkmcnt(0)
	v_mfma_f32_16x16x32_bf16 v[62:65], v[168:171], v[200:203], v[62:65]
	v_mfma_f32_16x16x32_bf16 v[58:61], v[176:179], v[200:203], v[58:61]
	v_mfma_f32_16x16x32_bf16 v[46:49], v[168:171], v[208:211], v[46:49]
	v_mfma_f32_16x16x32_bf16 v[42:45], v[176:179], v[208:211], v[42:45]
	v_mfma_f32_16x16x32_bf16 v[30:33], v[168:171], v[216:219], v[30:33]
	v_mfma_f32_16x16x32_bf16 v[26:29], v[176:179], v[216:219], v[26:29]
	v_mfma_f32_16x16x32_bf16 v[14:17], v[168:171], v[224:227], v[14:17]
	v_mfma_f32_16x16x32_bf16 v[10:13], v[176:179], v[224:227], v[10:13]
	v_mfma_f32_16x16x32_bf16 v[62:65], v[172:175], v[204:207], v[62:65]
	v_mfma_f32_16x16x32_bf16 v[58:61], v[180:183], v[204:207], v[58:61]
	v_mfma_f32_16x16x32_bf16 v[46:49], v[172:175], v[212:215], v[46:49]
	v_mfma_f32_16x16x32_bf16 v[42:45], v[180:183], v[212:215], v[42:45]
	v_mfma_f32_16x16x32_bf16 v[30:33], v[172:175], v[220:223], v[30:33]
	v_mfma_f32_16x16x32_bf16 v[26:29], v[180:183], v[220:223], v[26:29]
	v_mfma_f32_16x16x32_bf16 v[14:17], v[172:175], v[228:231], v[14:17]
	v_mfma_f32_16x16x32_bf16 v[10:13], v[180:183], v[228:231], v[10:13]
	s_setprio 0
	s_setprio 1
	v_mfma_f32_16x16x32_bf16 v[54:57], v[184:187], v[200:203], v[54:57]
	v_mfma_f32_16x16x32_bf16 v[50:53], v[192:195], v[200:203], v[50:53]
	v_mfma_f32_16x16x32_bf16 v[38:41], v[184:187], v[208:211], v[38:41]
	v_mfma_f32_16x16x32_bf16 v[34:37], v[192:195], v[208:211], v[34:37]
	v_mfma_f32_16x16x32_bf16 v[22:25], v[184:187], v[216:219], v[22:25]
	v_mfma_f32_16x16x32_bf16 v[18:21], v[192:195], v[216:219], v[18:21]
	v_mfma_f32_16x16x32_bf16 v[6:9], v[184:187], v[224:227], v[6:9]
	v_mfma_f32_16x16x32_bf16 v[2:5], v[192:195], v[224:227], v[2:5]
	v_mfma_f32_16x16x32_bf16 v[54:57], v[188:191], v[204:207], v[54:57]
	v_mfma_f32_16x16x32_bf16 v[50:53], v[196:199], v[204:207], v[50:53]
	v_mfma_f32_16x16x32_bf16 v[38:41], v[188:191], v[212:215], v[38:41]
	v_mfma_f32_16x16x32_bf16 v[34:37], v[196:199], v[212:215], v[34:37]
	v_mfma_f32_16x16x32_bf16 v[22:25], v[188:191], v[220:223], v[22:25]
	v_mfma_f32_16x16x32_bf16 v[18:21], v[196:199], v[220:223], v[18:21]
	v_mfma_f32_16x16x32_bf16 v[6:9], v[188:191], v[228:231], v[6:9]
	v_mfma_f32_16x16x32_bf16 v[2:5], v[196:199], v[228:231], v[2:5]
	s_setprio 0
	s_add_i32 s60, s60, 2
	s_add_u32 s6, s6, 0x100
	s_addc_u32 s7, s7, 0
	s_add_u32 s23, s23, 0x100
	s_addc_u32 s41, s41, 0
	s_cmp_gt_u32 s60, 13
	s_barrier
	s_cbranch_scc1 .LBB0_975

; #define PG8_STAGE(bufoff, gbase, voff) do { _Pragma("unroll") for (int _i = 0; _i < 2; ++_i) \
;         __builtin_amdgcn_global_load_lds((const unsigned*)((const char*)(gbase) + (voff)[_i]), (LAS unsigned*)(lds + (bufoff) + ldsw + _i * 8192), 16, 0, 0); } while (0)
; #define PG8_LDA(dst, b, h) do { _Pragma("unroll") for (int m = 0; m < 4; ++m) _Pragma("unroll") for (int k = 0; k < 2; ++k) dst[m][k] = *(const LAS bf16x8*)(lds + PG8_SA(b, h) + aoff + m * 2048 + k * 1024); } while (0)
; #define PG8_LDB(dst, b, h) do { _Pragma("unroll") for (int n = 0; n < 2; ++n) _Pragma("unroll") for (int k = 0; k < 2; ++k) dst[n][k] = *(const LAS bf16x8*)(lds + PG8_SB(b, h) + boff + n * 2048 + k * 1024); } while (0)
; #define PG8_MMA(ai, bj, At, Bt) do { __builtin_amdgcn_s_setprio(1); _Pragma("unroll") for (int m = 0; m < 4; ++m) _Pragma("unroll") for (int n = 0; n < 2; ++n) _Pragma("unroll") for (int k = 0; k < 2; ++k) \
;         acc[ai][bj][m][n] = __builtin_amdgcn_mfma_f32_16x16x32_bf16(Bt[n][k], At[m][k], acc[ai][bj][m][n], 0, 0, 0); __builtin_amdgcn_s_setprio(0); } while (0)
; #define PG8_WAIT_V(n) asm volatile("s_waitcnt vmcnt(" #n ")" ::: "memory")
; #define PG8_WAIT_L(n) asm volatile("s_waitcnt lgkmcnt(" #n ")" ::: "memory")
; #define PG8_BAR __builtin_amdgcn_s_barrier()
; #define PG8_SCHED __builtin_amdgcn_sched_barrier(0)
; template <class Epi, class Sched>
; __device__ __forceinline__ void gemm_phase(LAS unsigned char* lds, const int K, const Sched& S, const Epi& E) {
;     ...
;             if (last) E.prefetch(lds, cur, wid, lane);
;             const char* a1 = cA + (size_t)(t + 1) * kstep;
;             const char* a2 = last ? nA : cA + (size_t)(t + 2) * kstep; const char* b2 = last ? nB : cB + (size_t)(t + 2) * kstep;
;             const char* a3 = a2 + kstep; const char* b3 = b2 + kstep;
;             PG8_LDB(B0, 0, 0); PG8_LDB(B1, 0, 1); PG8_SCHED; PG8_LDA(At, 0, 0); PG8_STAGE(PG8_SA(1, 1), a1 + hstep, voffA);
;             PG8_WAIT_V(8); PG8_WAIT_L(0); PG8_BAR; PG8_MMA(0, 0, At, B0); PG8_MMA(0, 1, At, B1); PG8_BAR; PG8_SCHED;
;             PG8_LDA(At, 0, 1); PG8_STAGE(PG8_SB(0, 0), b2, voffB); PG8_STAGE(PG8_SB(0, 1), b2 + hstep, voffB); PG8_STAGE(PG8_SA(0, 0), a2, voffA);
;             PG8_WAIT_V(8); PG8_WAIT_L(0); PG8_BAR; PG8_MMA(1, 0, At, B0); PG8_MMA(1, 1, At, B1); PG8_BAR; PG8_SCHED;
.LBB0_1053:
	ds_read_b128 v[164:167], v148
	ds_read_b128 v[168:171], v149
	ds_read_b128 v[172:175], v150
	ds_read_b128 v[176:179], v151
	ds_read_b128 v[180:183], v152
	ds_read_b128 v[184:187], v153
	ds_read_b128 v[188:191], v154
	ds_read_b128 v[192:195], v155
	s_add_u32 s48, s42, s46
	s_addc_u32 s49, s43, s47
	s_add_u32 s48, s48, 0x100
	s_addc_u32 s49, s49, 0
	s_add_u32 s72, s69, s46
	s_addc_u32 s73, s70, s47
	s_cmpk_eq_i32 s46, 0x1500
	s_cselect_b32 s51, s27, s49
	s_cselect_b32 s50, s26, s48
	s_cselect_b32 s49, s41, s73
	s_cselect_b32 s48, s40, s72
	s_mov_b32 m0, s63
	v_lshl_add_u64 v[196:197], v[142:143], 0, s[46:47]
	ds_read_b128 v[200:203], v147
	ds_read_b128 v[204:207], v147 offset:1024
	ds_read_b128 v[208:211], v147 offset:2048
	ds_read_b128 v[212:215], v147 offset:3072
	ds_read_b128 v[216:219], v147 offset:4096
	ds_read_b128 v[220:223], v147 offset:5120
	ds_read_b128 v[224:227], v147 offset:6144
	ds_read_b128 v[228:231], v147 offset:7168
	global_load_lds_dwordx4 v[196:197], off
	v_lshl_add_u64 v[196:197], v[144:145], 0, s[46:47]
	s_mov_b32 m0, s64
	s_nop 0
	global_load_lds_dwordx4 v[196:197], off
	s_waitcnt vmcnt(8)
	s_waitcnt lgkmcnt(0)
	s_barrier
	s_setprio 1
	s_waitcnt lgkmcnt(0)
	v_mfma_f32_16x16x32_bf16 v[126:129], v[164:167], v[200:203], v[126:129]
	v_mfma_f32_16x16x32_bf16 v[122:125], v[172:175], v[200:203], v[122:125]
	v_mfma_f32_16x16x32_bf16 v[110:113], v[164:167], v[208:211], v[110:113]
	v_mfma_f32_16x16x32_bf16 v[106:109], v[172:175], v[208:211], v[106:109]
	v_mfma_f32_16x16x32_bf16 v[94:97], v[164:167], v[216:219], v[94:97]
	v_mfma_f32_16x16x32_bf16 v[90:93], v[172:175], v[216:219], v[90:93]
	v_mfma_f32_16x16x32_bf16 v[78:81], v[164:167], v[224:227], v[78:81]
	v_mfma_f32_16x16x32_bf16 v[74:77], v[172:175], v[224:227], v[74:77]
	v_mfma_f32_16x16x32_bf16 v[126:129], v[168:171], v[204:207], v[126:129]
	v_mfma_f32_16x16x32_bf16 v[122:125], v[176:179], v[204:207], v[122:125]
	v_mfma_f32_16x16x32_bf16 v[110:113], v[168:171], v[212:215], v[110:113]
	v_mfma_f32_16x16x32_bf16 v[106:109], v[176:179], v[212:215], v[106:109]
	v_mfma_f32_16x16x32_bf16 v[94:97], v[168:171], v[220:223], v[94:97]
	v_mfma_f32_16x16x32_bf16 v[90:93], v[176:179], v[220:223], v[90:93]
	v_mfma_f32_16x16x32_bf16 v[78:81], v[168:171], v[228:231], v[78:81]
	v_mfma_f32_16x16x32_bf16 v[74:77], v[176:179], v[228:231], v[74:77]
	s_setprio 0
	s_setprio 1
	v_mfma_f32_16x16x32_bf16 v[118:121], v[180:183], v[200:203], v[118:121]
	v_mfma_f32_16x16x32_bf16 v[114:117], v[188:191], v[200:203], v[114:117]
	v_mfma_f32_16x16x32_bf16 v[102:105], v[180:183], v[208:211], v[102:105]
	v_mfma_f32_16x16x32_bf16 v[98:101], v[188:191], v[208:211], v[98:101]
	v_mfma_f32_16x16x32_bf16 v[86:89], v[180:183], v[216:219], v[86:89]
	v_mfma_f32_16x16x32_bf16 v[82:85], v[188:191], v[216:219], v[82:85]
	v_mfma_f32_16x16x32_bf16 v[70:73], v[180:183], v[224:227], v[70:73]
	v_mfma_f32_16x16x32_bf16 v[66:69], v[188:191], v[224:227], v[66:69]
	v_mfma_f32_16x16x32_bf16 v[118:121], v[184:187], v[204:207], v[118:121]
	v_mfma_f32_16x16x32_bf16 v[114:117], v[192:195], v[204:207], v[114:117]
	v_mfma_f32_16x16x32_bf16 v[102:105], v[184:187], v[212:215], v[102:105]
	v_mfma_f32_16x16x32_bf16 v[98:101], v[192:195], v[212:215], v[98:101]
	v_mfma_f32_16x16x32_bf16 v[86:89], v[184:187], v[220:223], v[86:89]
	v_mfma_f32_16x16x32_bf16 v[82:85], v[192:195], v[220:223], v[82:85]
	v_mfma_f32_16x16x32_bf16 v[70:73], v[184:187], v[228:231], v[70:73]
	v_mfma_f32_16x16x32_bf16 v[66:69], v[192:195], v[228:231], v[66:69]
	s_setprio 0
	s_barrier
	s_mov_b32 m0, s38
	v_lshl_add_u64 v[196:197], s[48:49], 0, v[132:133]
	s_add_u32 s72, s48, 0xb0000
	ds_read_b128 v[200:203], v147 offset:16384
	ds_read_b128 v[204:207], v147 offset:17408
	ds_read_b128 v[208:211], v147 offset:18432
	ds_read_b128 v[212:215], v147 offset:19456
	ds_read_b128 v[216:219], v147 offset:20480
	ds_read_b128 v[220:223], v147 offset:21504
	ds_read_b128 v[224:227], v147 offset:22528
	ds_read_b128 v[228:231], v147 offset:23552
	global_load_lds_dwordx4 v[196:197], off
	v_lshl_add_u64 v[232:233], s[48:49], 0, v[136:137]
	s_mov_b32 m0, s39
	s_addc_u32 s73, s49, 0
	global_load_lds_dwordx4 v[232:233], off
	v_lshl_add_u64 v[234:235], s[72:73], 0, v[132:133]
	s_mov_b32 m0, s52
	v_lshl_add_u64 v[236:237], s[50:51], 0, v[134:135]
	global_load_lds_dwordx4 v[234:235], off
	v_lshl_add_u64 v[234:235], s[72:73], 0, v[136:137]
	s_mov_b32 m0, s53
	s_nop 0
	global_load_lds_dwordx4 v[234:235], off
	v_lshl_add_u64 v[234:235], s[50:51], 0, v[130:131]
	s_mov_b32 m0, s37
	s_nop 0
	global_load_lds_dwordx4 v[234:235], off
	s_mov_b32 m0, s54
	s_nop 0
	global_load_lds_dwordx4 v[236:237], off
	s_waitcnt vmcnt(8)
	s_waitcnt lgkmcnt(0)
	s_barrier
; #define PG8_STAGE(bufoff, gbase, voff) do { _Pragma("unroll") for (int _i = 0; _i < 2; ++_i) \
;         __builtin_amdgcn_global_load_lds((const unsigned*)((const char*)(gbase) + (voff)[_i]), (LAS unsigned*)(lds + (bufoff) + ldsw + _i * 8192), 16, 0, 0); } while (0)
; #define PG8_LDA(dst, b, h) do { _Pragma("unroll") for (int m = 0; m < 4; ++m) _Pragma("unroll") for (int k = 0; k < 2; ++k) dst[m][k] = *(const LAS bf16x8*)(lds + PG8_SA(b, h) + aoff + m * 2048 + k * 1024); } while (0)
; #define PG8_LDB(dst, b, h) do { _Pragma("unroll") for (int n = 0; n < 2; ++n) _Pragma("unroll") for (int k = 0; k < 2; ++k) dst[n][k] = *(const LAS bf16x8*)(lds + PG8_SB(b, h) + boff + n * 2048 + k * 1024); } while (0)
; #define PG8_MMA(ai, bj, At, Bt) do { __builtin_amdgcn_s_setprio(1); _Pragma("unroll") for (int m = 0; m < 4; ++m) _Pragma("unroll") for (int n = 0; n < 2; ++n) _Pragma("unroll") for (int k = 0; k < 2; ++k) \
;         acc[ai][bj][m][n] = __builtin_amdgcn_mfma_f32_16x16x32_bf16(Bt[n][k], At[m][k], acc[ai][bj][m][n], 0, 0, 0); __builtin_amdgcn_s_setprio(0); } while (0)
; #define PG8_WAIT_V(n) asm volatile("s_waitcnt vmcnt(" #n ")" ::: "memory")
; #define PG8_WAIT_L(n) asm volatile("s_waitcnt lgkmcnt(" #n ")" ::: "memory")
; #define PG8_BAR __builtin_amdgcn_s_barrier()
; #define PG8_SCHED __builtin_amdgcn_sched_barrier(0)
; template <class Epi, class Sched>
; __device__ __forceinline__ void gemm_phase(LAS unsigned char* lds, const int K, const Sched& S, const Epi& E) {
;     ...
;             PG8_WAIT_V(8); PG8_WAIT_L(0); PG8_BAR; PG8_MMA(1, 0, At, B0); PG8_MMA(1, 1, At, B1); PG8_BAR; PG8_SCHED;
;             PG8_LDB(B0, 1, 0); PG8_LDB(B1, 1, 1); PG8_SCHED; PG8_LDA(At, 1, 0); PG8_STAGE(PG8_SA(0, 1), a2 + hstep, voffA);
;             PG8_WAIT_V(8); PG8_WAIT_L(0); PG8_BAR; PG8_MMA(0, 0, At, B0); PG8_MMA(0, 1, At, B1); PG8_BAR; PG8_SCHED;
	s_setprio 1
	s_waitcnt lgkmcnt(0)
	v_mfma_f32_16x16x32_bf16 v[62:65], v[164:167], v[200:203], v[62:65]
	v_mfma_f32_16x16x32_bf16 v[58:61], v[172:175], v[200:203], v[58:61]
	v_mfma_f32_16x16x32_bf16 v[46:49], v[164:167], v[208:211], v[46:49]
	v_mfma_f32_16x16x32_bf16 v[42:45], v[172:175], v[208:211], v[42:45]
	v_mfma_f32_16x16x32_bf16 v[30:33], v[164:167], v[216:219], v[30:33]
	v_mfma_f32_16x16x32_bf16 v[26:29], v[172:175], v[216:219], v[26:29]
	v_mfma_f32_16x16x32_bf16 v[14:17], v[164:167], v[224:227], v[14:17]
	v_mfma_f32_16x16x32_bf16 v[10:13], v[172:175], v[224:227], v[10:13]
	v_mfma_f32_16x16x32_bf16 v[62:65], v[168:171], v[204:207], v[62:65]
	v_mfma_f32_16x16x32_bf16 v[58:61], v[176:179], v[204:207], v[58:61]
	v_mfma_f32_16x16x32_bf16 v[46:49], v[168:171], v[212:215], v[46:49]
	v_mfma_f32_16x16x32_bf16 v[42:45], v[176:179], v[212:215], v[42:45]
	v_mfma_f32_16x16x32_bf16 v[30:33], v[168:171], v[220:223], v[30:33]
	v_mfma_f32_16x16x32_bf16 v[26:29], v[176:179], v[220:223], v[26:29]
	v_mfma_f32_16x16x32_bf16 v[14:17], v[168:171], v[228:231], v[14:17]
	v_mfma_f32_16x16x32_bf16 v[10:13], v[176:179], v[228:231], v[10:13]
	s_setprio 0
	s_setprio 1
	v_mfma_f32_16x16x32_bf16 v[54:57], v[180:183], v[200:203], v[54:57]
	v_mfma_f32_16x16x32_bf16 v[50:53], v[188:191], v[200:203], v[50:53]
	v_mfma_f32_16x16x32_bf16 v[38:41], v[180:183], v[208:211], v[38:41]
	v_mfma_f32_16x16x32_bf16 v[34:37], v[188:191], v[208:211], v[34:37]
	v_mfma_f32_16x16x32_bf16 v[22:25], v[180:183], v[216:219], v[22:25]
	v_mfma_f32_16x16x32_bf16 v[18:21], v[188:191], v[216:219], v[18:21]
	v_mfma_f32_16x16x32_bf16 v[6:9], v[180:183], v[224:227], v[6:9]
	v_mfma_f32_16x16x32_bf16 v[2:5], v[188:191], v[224:227], v[2:5]
	v_mfma_f32_16x16x32_bf16 v[54:57], v[184:187], v[204:207], v[54:57]
	v_mfma_f32_16x16x32_bf16 v[50:53], v[192:195], v[204:207], v[50:53]
	v_mfma_f32_16x16x32_bf16 v[38:41], v[184:187], v[212:215], v[38:41]
	v_mfma_f32_16x16x32_bf16 v[34:37], v[192:195], v[212:215], v[34:37]
	v_mfma_f32_16x16x32_bf16 v[22:25], v[184:187], v[220:223], v[22:25]
	v_mfma_f32_16x16x32_bf16 v[18:21], v[192:195], v[220:223], v[18:21]
	v_mfma_f32_16x16x32_bf16 v[6:9], v[184:187], v[228:231], v[6:9]
	v_mfma_f32_16x16x32_bf16 v[2:5], v[192:195], v[228:231], v[2:5]
	s_setprio 0
	s_barrier
	ds_read_b128 v[164:167], v156
	ds_read_b128 v[168:171], v157
	ds_read_b128 v[172:175], v158
	ds_read_b128 v[176:179], v159
	ds_read_b128 v[180:183], v160
	ds_read_b128 v[184:187], v161
	ds_read_b128 v[188:191], v162
	ds_read_b128 v[192:195], v163
	s_add_u32 s50, s50, 0xb0000
	s_addc_u32 s51, s51, 0
	s_mov_b32 m0, s55
	v_lshl_add_u64 v[240:241], s[50:51], 0, v[130:131]
	ds_read_b128 v[200:203], v147 offset:32768
	ds_read_b128 v[204:207], v147 offset:33792
	ds_read_b128 v[208:211], v147 offset:34816
	ds_read_b128 v[212:215], v147 offset:35840
	ds_read_b128 v[216:219], v147 offset:36864
	ds_read_b128 v[220:223], v147 offset:37888
	ds_read_b128 v[224:227], v147 offset:38912
	ds_read_b128 v[228:231], v147 offset:39936
	global_load_lds_dwordx4 v[240:241], off
	v_lshl_add_u64 v[240:241], s[50:51], 0, v[134:135]
	s_mov_b32 m0, s56
	s_nop 0
	global_load_lds_dwordx4 v[240:241], off
	s_waitcnt vmcnt(8)
	s_waitcnt lgkmcnt(0)
	s_barrier
	s_setprio 1
	s_waitcnt lgkmcnt(0)
	v_mfma_f32_16x16x32_bf16 v[126:129], v[164:167], v[200:203], v[126:129]
	v_mfma_f32_16x16x32_bf16 v[122:125], v[172:175], v[200:203], v[122:125]
	v_mfma_f32_16x16x32_bf16 v[110:113], v[164:167], v[208:211], v[110:113]
	v_mfma_f32_16x16x32_bf16 v[106:109], v[172:175], v[208:211], v[106:109]
	v_mfma_f32_16x16x32_bf16 v[94:97], v[164:167], v[216:219], v[94:97]
	v_mfma_f32_16x16x32_bf16 v[90:93], v[172:175], v[216:219], v[90:93]
	v_mfma_f32_16x16x32_bf16 v[78:81], v[164:167], v[224:227], v[78:81]
	v_mfma_f32_16x16x32_bf16 v[74:77], v[172:175], v[224:227], v[74:77]
	v_mfma_f32_16x16x32_bf16 v[126:129], v[168:171], v[204:207], v[126:129]
	v_mfma_f32_16x16x32_bf16 v[122:125], v[176:179], v[204:207], v[122:125]
	v_mfma_f32_16x16x32_bf16 v[110:113], v[168:171], v[212:215], v[110:113]
	v_mfma_f32_16x16x32_bf16 v[106:109], v[176:179], v[212:215], v[106:109]
	v_mfma_f32_16x16x32_bf16 v[94:97], v[168:171], v[220:223], v[94:97]
	v_mfma_f32_16x16x32_bf16 v[90:93], v[176:179], v[220:223], v[90:93]
	v_mfma_f32_16x16x32_bf16 v[78:81], v[168:171], v[228:231], v[78:81]
	v_mfma_f32_16x16x32_bf16 v[74:77], v[176:179], v[228:231], v[74:77]
	s_setprio 0
	s_setprio 1
	v_mfma_f32_16x16x32_bf16 v[118:121], v[180:183], v[200:203], v[118:121]
	v_mfma_f32_16x16x32_bf16 v[114:117], v[188:191], v[200:203], v[114:117]
	v_mfma_f32_16x16x32_bf16 v[102:105], v[180:183], v[208:211], v[102:105]
	v_mfma_f32_16x16x32_bf16 v[98:101], v[188:191], v[208:211], v[98:101]
	v_mfma_f32_16x16x32_bf16 v[86:89], v[180:183], v[216:219], v[86:89]
	v_mfma_f32_16x16x32_bf16 v[82:85], v[188:191], v[216:219], v[82:85]
	v_mfma_f32_16x16x32_bf16 v[70:73], v[180:183], v[224:227], v[70:73]
	v_mfma_f32_16x16x32_bf16 v[66:69], v[188:191], v[224:227], v[66:69]
	v_mfma_f32_16x16x32_bf16 v[118:121], v[184:187], v[204:207], v[118:121]
	v_mfma_f32_16x16x32_bf16 v[114:117], v[192:195], v[204:207], v[114:117]
	v_mfma_f32_16x16x32_bf16 v[102:105], v[184:187], v[212:215], v[102:105]
	v_mfma_f32_16x16x32_bf16 v[98:101], v[192:195], v[212:215], v[98:101]
	v_mfma_f32_16x16x32_bf16 v[86:89], v[184:187], v[220:223], v[86:89]
	v_mfma_f32_16x16x32_bf16 v[82:85], v[192:195], v[220:223], v[82:85]
	v_mfma_f32_16x16x32_bf16 v[70:73], v[184:187], v[228:231], v[70:73]
	v_mfma_f32_16x16x32_bf16 v[66:69], v[192:195], v[228:231], v[66:69]
	s_setprio 0
	s_barrier
; #define PG8_STAGE(bufoff, gbase, voff) do { _Pragma("unroll") for (int _i = 0; _i < 2; ++_i) \
;         __builtin_amdgcn_global_load_lds((const unsigned*)((const char*)(gbase) + (voff)[_i]), (LAS unsigned*)(lds + (bufoff) + ldsw + _i * 8192), 16, 0, 0); } while (0)
; #define PG8_LDA(dst, b, h) do { _Pragma("unroll") for (int m = 0; m < 4; ++m) _Pragma("unroll") for (int k = 0; k < 2; ++k) dst[m][k] = *(const LAS bf16x8*)(lds + PG8_SA(b, h) + aoff + m * 2048 + k * 1024); } while (0)
; #define PG8_MMA(ai, bj, At, Bt) do { __builtin_amdgcn_s_setprio(1); _Pragma("unroll") for (int m = 0; m < 4; ++m) _Pragma("unroll") for (int n = 0; n < 2; ++n) _Pragma("unroll") for (int k = 0; k < 2; ++k) \
;         acc[ai][bj][m][n] = __builtin_amdgcn_mfma_f32_16x16x32_bf16(Bt[n][k], At[m][k], acc[ai][bj][m][n], 0, 0, 0); __builtin_amdgcn_s_setprio(0); } while (0)
; #define PG8_WAIT_V(n) asm volatile("s_waitcnt vmcnt(" #n ")" ::: "memory")
; #define PG8_WAIT_L(n) asm volatile("s_waitcnt lgkmcnt(" #n ")" ::: "memory")
; #define PG8_BAR __builtin_amdgcn_s_barrier()
; #define PG8_SCHED __builtin_amdgcn_sched_barrier(0)
; template <class Epi, class Sched>
; __device__ __forceinline__ void gemm_phase(LAS unsigned char* lds, const int K, const Sched& S, const Epi& E) {
;     ...
;             PG8_LDA(At, 1, 1); PG8_STAGE(PG8_SB(1, 0), b3, voffB); PG8_STAGE(PG8_SB(1, 1), b3 + hstep, voffB); PG8_STAGE(PG8_SA(1, 0), a3, voffA);
;             PG8_WAIT_V(8); PG8_WAIT_L(0); PG8_BAR; PG8_MMA(1, 0, At, B0); PG8_MMA(1, 1, At, B1); PG8_BAR; PG8_SCHED;
;         }
	s_mov_b32 m0, s57
	v_lshl_add_u64 v[196:197], v[196:197], 0, s[10:11]
	s_add_u32 s48, s48, 0xb0080
	ds_read_b128 v[200:203], v147 offset:49152
	ds_read_b128 v[204:207], v147 offset:50176
	ds_read_b128 v[208:211], v147 offset:51200
	ds_read_b128 v[212:215], v147 offset:52224
	ds_read_b128 v[216:219], v147 offset:53248
	ds_read_b128 v[220:223], v147 offset:54272
	ds_read_b128 v[224:227], v147 offset:55296
	ds_read_b128 v[228:231], v147 offset:56320
	global_load_lds_dwordx4 v[196:197], off
	v_lshl_add_u64 v[196:197], v[232:233], 0, s[10:11]
	s_mov_b32 m0, s58
	s_addc_u32 s49, s49, 0
	global_load_lds_dwordx4 v[196:197], off
	v_lshl_add_u64 v[196:197], s[48:49], 0, v[132:133]
	s_mov_b32 m0, s61
	s_nop 0
	global_load_lds_dwordx4 v[196:197], off
	v_lshl_add_u64 v[196:197], s[48:49], 0, v[136:137]
	s_mov_b32 m0, s62
	s_nop 0
	global_load_lds_dwordx4 v[196:197], off
	v_lshl_add_u64 v[196:197], v[234:235], 0, s[10:11]
	s_mov_b32 m0, s59
	s_nop 0
	global_load_lds_dwordx4 v[196:197], off
	v_lshl_add_u64 v[196:197], v[236:237], 0, s[10:11]
	s_mov_b32 m0, s60
	s_nop 0
	global_load_lds_dwordx4 v[196:197], off
	s_waitcnt vmcnt(8)
	s_waitcnt lgkmcnt(0)
	s_barrier
	s_setprio 1
	s_waitcnt lgkmcnt(0)
	v_mfma_f32_16x16x32_bf16 v[62:65], v[164:167], v[200:203], v[62:65]
	v_mfma_f32_16x16x32_bf16 v[58:61], v[172:175], v[200:203], v[58:61]
	v_mfma_f32_16x16x32_bf16 v[46:49], v[164:167], v[208:211], v[46:49]
	v_mfma_f32_16x16x32_bf16 v[42:45], v[172:175], v[208:211], v[42:45]
	v_mfma_f32_16x16x32_bf16 v[30:33], v[164:167], v[216:219], v[30:33]
	v_mfma_f32_16x16x32_bf16 v[26:29], v[172:175], v[216:219], v[26:29]
	v_mfma_f32_16x16x32_bf16 v[14:17], v[164:167], v[224:227], v[14:17]
	v_mfma_f32_16x16x32_bf16 v[10:13], v[172:175], v[224:227], v[10:13]
	v_mfma_f32_16x16x32_bf16 v[62:65], v[168:171], v[204:207], v[62:65]
	v_mfma_f32_16x16x32_bf16 v[58:61], v[176:179], v[204:207], v[58:61]
	v_mfma_f32_16x16x32_bf16 v[46:49], v[168:171], v[212:215], v[46:49]
	v_mfma_f32_16x16x32_bf16 v[42:45], v[176:179], v[212:215], v[42:45]
	v_mfma_f32_16x16x32_bf16 v[30:33], v[168:171], v[220:223], v[30:33]
	v_mfma_f32_16x16x32_bf16 v[26:29], v[176:179], v[220:223], v[26:29]
	v_mfma_f32_16x16x32_bf16 v[14:17], v[168:171], v[228:231], v[14:17]
	v_mfma_f32_16x16x32_bf16 v[10:13], v[176:179], v[228:231], v[10:13]
	s_setprio 0
	s_setprio 1
	v_mfma_f32_16x16x32_bf16 v[54:57], v[180:183], v[200:203], v[54:57]
	v_mfma_f32_16x16x32_bf16 v[50:53], v[188:191], v[200:203], v[50:53]
	v_mfma_f32_16x16x32_bf16 v[38:41], v[180:183], v[208:211], v[38:41]
	v_mfma_f32_16x16x32_bf16 v[34:37], v[188:191], v[208:211], v[34:37]
	v_mfma_f32_16x16x32_bf16 v[22:25], v[180:183], v[216:219], v[22:25]
	v_mfma_f32_16x16x32_bf16 v[18:21], v[188:191], v[216:219], v[18:21]
	v_mfma_f32_16x16x32_bf16 v[6:9], v[180:183], v[224:227], v[6:9]
	v_mfma_f32_16x16x32_bf16 v[2:5], v[188:191], v[224:227], v[2:5]
	v_mfma_f32_16x16x32_bf16 v[54:57], v[184:187], v[204:207], v[54:57]
	v_mfma_f32_16x16x32_bf16 v[50:53], v[192:195], v[204:207], v[50:53]
	v_mfma_f32_16x16x32_bf16 v[38:41], v[184:187], v[212:215], v[38:41]
	v_mfma_f32_16x16x32_bf16 v[34:37], v[192:195], v[212:215], v[34:37]
	v_mfma_f32_16x16x32_bf16 v[22:25], v[184:187], v[220:223], v[22:25]
	v_mfma_f32_16x16x32_bf16 v[18:21], v[192:195], v[220:223], v[18:21]
	v_mfma_f32_16x16x32_bf16 v[6:9], v[184:187], v[228:231], v[6:9]
	v_mfma_f32_16x16x32_bf16 v[2:5], v[192:195], v[228:231], v[2:5]
	s_setprio 0
	s_add_i32 s71, s71, 2
	s_add_u32 s46, s46, 0x100
	s_addc_u32 s47, s47, 0
	s_cmp_gt_u32 s71, 41
	s_barrier
	s_cbranch_scc0 .LBB0_1053
	s_and_b64 vcc, exec, s[22:23]
	s_cbranch_vccz .LBB0_1056
	s_barrier
